# GLU epilogue: drop dead zero-inits before full-mask DPP row rotates
# speedup vs baseline: 1.0043x; 1.0002x over previous
;     __device__ __forceinline__ void operator()(const pg8::f32x4 (&acc)[2][2][4][2], const pg8::Unit& u, int wr, int wc, int fr, int fq) const {
;     ...
;         float w0[8], w1[8], w2[8], bb[8];
; #pragma unroll
;         for (int hq = 0; hq < 2; ++hq) { const pg8::f32x4 q0 = *(const pg8::f32x4*)(cw + ch0 + 4 * hq), q1 = *(const pg8::f32x4*)(cw + DFF + ch0 + 4 * hq), q2 = *(const pg8::f32x4*)(cw + 2 * DFF + ch0 + 4 * hq), q3 = *(const pg8::f32x4*)(cb + ch0 + 4 * hq);
; #pragma unroll
;             for (int e = 0; e < 4; ++e) { w0[4 * hq + e] = q0[e]; w1[4 * hq + e] = q1[e]; w2[4 * hq + e] = q2[e]; bb[4 * hq + e] = q3[e]; } }
; #pragma unroll
;         for (int ai = 0; ai < 2; ++ai) {
;             const int kb = u.pm * 4 + ai * 2 + wr;
;             float ruP[8], rdC[8];
; #pragma unroll
;             for (int c = 0; c < 8; ++c) { ruP[c] = 0.f; rdC[c] = dpp_rol1(acc[ai][0][0][c >> 2][c & 3]); }
; #pragma unroll
;             for (int m = 0; m < 4; ++m) {
;                 const int rl = 16 * m + fr, gr = 62 * kb - 1 + rl;
;                 bool first, last; if (gr < ML) { const int t = gr & 8191; first = t == 0; last = t == 8191; } else { const int t = (gr - ML) & 255; first = t == 0; last = t == 255; }
;                 float res[8];
; #pragma unroll
;                 for (int c = 0; c < 8; ++c) {
;                     const int n = c >> 2, e = c & 3;
;                     const float x0 = acc[ai][0][m][n][e];
;                     const float ruC = dpp_ror1(x0), rdN = m < 3 ? dpp_rol1(acc[ai][0][m < 3 ? m + 1 : 3][n][e]) : 0.f;
;                     float xu = fr == 0 ? ruP[c] : ruC, xd = fr == 15 ? rdN : rdC[c];
;                     xu = first ? 0.f : xu; xd = last ? 0.f : xd;
;                     ruP[c] = ruC; rdC[c] = rdN;
;                     const float x = w0[c] * xu + w1[c] * x0 + w2[c] * xd + bb[c];
;                     const float u2 = -2.302208198f * (x + 0.044715f * x * x * x);
;                     res[c] = x * __builtin_amdgcn_rcpf(1.0f + __builtin_amdgcn_exp2f(u2)) * acc[ai][1][m][n][e];
;                 }
;                 if (rl >= 1 && rl <= 62 && gr < nrows) { v4u o; o.x = pk2(res[0], res[1]); o.y = pk2(res[2], res[3]); o.z = pk2(res[4], res[5]); o.w = pk2(res[6], res[7]);
;                     *(v4u*)(G + (size_t)gr * DFF + ch0) = o; }
.LBB0_1084:
	v_lshl_or_b32 v170, s52, 7, v177
	v_ashrrev_i32_e32 v171, 31, v170
	v_lshlrev_b64 v[56:57], 2, v[170:171]
	v_lshl_add_u64 v[60:61], s[10:11], 0, v[56:57]
	v_lshl_add_u64 v[62:63], s[68:69], 0, v[56:57]
	v_lshl_add_u64 v[64:65], s[70:71], 0, v[56:57]
	v_lshl_add_u64 v[84:85], s[36:37], 0, v[56:57]
	global_load_dwordx4 v[56:59], v[60:61], off offset:16
	global_load_dwordx4 v[76:79], v[60:61], off
	global_load_dwordx4 v[68:71], v[62:63], off offset:16
	global_load_dwordx4 v[92:95], v[62:63], off
	s_nop 0
	global_load_dwordx4 v[60:63], v[64:65], off offset:16
	global_load_dwordx4 v[80:83], v[64:65], off
	s_nop 0
	global_load_dwordx4 v[64:67], v[84:85], off offset:16
	s_nop 0
	global_load_dwordx4 v[84:87], v[84:85], off
	s_lshl_b32 s12, s65, 2
	s_add_i32 s65, s12, s88
	s_mul_i32 s65, s65, 62
	s_add_i32 s73, s65, -1
	v_add_u32_e32 v194, s73, v172
	v_cmp_gt_i32_e32 vcc, s86, v194
	v_mov_b32_dpp v198, v152 row_ror:15 row_mask:0xf bank_mask:0xf
	v_mov_b32_dpp v199, v153 row_ror:15 row_mask:0xf bank_mask:0xf
	v_mov_b32_dpp v200, v154 row_ror:15 row_mask:0xf bank_mask:0xf
	v_mov_b32_dpp v201, v155 row_ror:15 row_mask:0xf bank_mask:0xf
	v_mov_b32_dpp v202, v156 row_ror:15 row_mask:0xf bank_mask:0xf
	v_mov_b32_dpp v203, v157 row_ror:15 row_mask:0xf bank_mask:0xf
	v_mov_b32_dpp v196, v158 row_ror:15 row_mask:0xf bank_mask:0xf
	v_mov_b32_dpp v197, v159 row_ror:15 row_mask:0xf bank_mask:0xf
	v_mov_b32_dpp v184, v152 row_ror:1 row_mask:0xf bank_mask:0xf
	v_mov_b32_dpp v183, v140 row_ror:15 row_mask:0xf bank_mask:0xf
	v_mov_b32_dpp v181, v153 row_ror:1 row_mask:0xf bank_mask:0xf
	v_mov_b32_dpp v179, v141 row_ror:15 row_mask:0xf bank_mask:0xf
	v_mov_b32_dpp v188, v154 row_ror:1 row_mask:0xf bank_mask:0xf
	v_mov_b32_dpp v187, v142 row_ror:15 row_mask:0xf bank_mask:0xf
	v_mov_b32_dpp v186, v155 row_ror:1 row_mask:0xf bank_mask:0xf
	v_mov_b32_dpp v185, v143 row_ror:15 row_mask:0xf bank_mask:0xf
	v_mov_b32_dpp v192, v156 row_ror:1 row_mask:0xf bank_mask:0xf
	v_mov_b32_dpp v191, v136 row_ror:15 row_mask:0xf bank_mask:0xf
	v_mov_b32_dpp v190, v157 row_ror:1 row_mask:0xf bank_mask:0xf
	v_mov_b32_dpp v189, v137 row_ror:15 row_mask:0xf bank_mask:0xf
	v_mov_b32_dpp v195, v158 row_ror:1 row_mask:0xf bank_mask:0xf
	v_mov_b32_dpp v193, v138 row_ror:15 row_mask:0xf bank_mask:0xf
	v_mov_b32_dpp v182, v159 row_ror:1 row_mask:0xf bank_mask:0xf
	v_mov_b32_dpp v180, v139 row_ror:15 row_mask:0xf bank_mask:0xf
	s_and_b64 s[48:49], s[42:43], vcc
	s_and_saveexec_b64 s[52:53], s[48:49]
	s_movk_i32 s12, 0xff
	s_movk_i32 s78, 0x1fff
	s_cbranch_execz .LBB0_1086
	v_and_b32_e32 v204, 0x1fff, v194
	v_and_b32_e32 v205, 0xff, v194
	v_cmp_gt_i32_e32 vcc, s97, v194
	v_cmp_eq_u32_e64 s[48:49], s78, v204
	s_waitcnt vmcnt(0)
	v_pk_mul_f32 v[156:157], v[156:157], v[68:69]
	v_cndmask_b32_e32 v206, v205, v204, vcc
	v_cndmask_b32_e64 v204, 0, 1, s[48:49]
	v_cmp_eq_u32_e64 s[48:49], s12, v205
	v_cndmask_b32_e64 v202, v202, v191, s[40:41]
	v_cndmask_b32_e64 v203, v203, v189, s[40:41]
	v_cndmask_b32_e64 v205, 0, 1, s[48:49]
	v_cndmask_b32_e32 v204, v205, v204, vcc
	v_and_b32_e32 v207, 1, v204
	v_cmp_eq_u32_e32 vcc, 0, v206
	v_cmp_eq_u32_e64 s[48:49], 1, v207
	v_pk_mul_f32 v[152:153], v[152:153], v[92:93]
	v_cndmask_b32_e64 v205, v190, 0, vcc
	v_cndmask_b32_e64 v204, v192, 0, vcc
	v_pk_fma_f32 v[156:157], v[56:57], v[204:205], v[156:157]
	v_cndmask_b32_e64 v203, v203, 0, s[48:49]
	v_cndmask_b32_e64 v202, v202, 0, s[48:49]
	v_pk_fma_f32 v[156:157], v[60:61], v[202:203], v[156:157]
	v_cndmask_b32_e64 v198, v198, v183, s[40:41]
	v_pk_add_f32 v[156:157], v[64:65], v[156:157]
	v_cndmask_b32_e64 v199, v199, v179, s[40:41]
	v_mul_f32_e32 v202, 0x3d372713, v156
	v_mul_f32_e32 v203, 0x3d372713, v157
	v_mul_f32_e32 v202, v156, v202
	v_mul_f32_e32 v203, v157, v203
	v_fma_f32 v202, v156, v202, v156
	v_fma_f32 v203, v157, v203, v157
	v_mul_f32_e32 v202, 0xc0135761, v202
	v_mul_f32_e32 v203, 0xc0135761, v203
	v_exp_f32_e32 v202, v202
	v_exp_f32_e32 v203, v203
	v_cndmask_b32_e64 v199, v199, 0, s[48:49]
	v_cndmask_b32_e64 v198, v198, 0, s[48:49]
	v_add_f32_e32 v202, 1.0, v202
	v_add_f32_e32 v203, 1.0, v203
	v_rcp_f32_e32 v202, v202
	v_rcp_f32_e32 v203, v203
	v_pk_mul_f32 v[158:159], v[158:159], v[70:71]
	v_cndmask_b32_e64 v196, v196, v193, s[40:41]
	v_cndmask_b32_e64 v197, v197, v180, s[40:41]
	v_pk_mul_f32 v[156:157], v[156:157], v[202:203]
	v_cndmask_b32_e64 v197, v197, 0, s[48:49]
	v_pk_mul_f32 v[156:157], v[144:145], v[156:157]
	v_pk_mul_f32 v[144:145], v[154:155], v[94:95]
	v_cndmask_b32_e64 v155, v186, 0, vcc
	v_cndmask_b32_e64 v154, v188, 0, vcc
	v_pk_fma_f32 v[144:145], v[78:79], v[154:155], v[144:145]
	v_cndmask_b32_e64 v154, v200, v187, s[40:41]
	v_cndmask_b32_e64 v155, v201, v185, s[40:41]
	v_cndmask_b32_e64 v155, v155, 0, s[48:49]
	v_cndmask_b32_e64 v154, v154, 0, s[48:49]
	v_pk_fma_f32 v[144:145], v[82:83], v[154:155], v[144:145]
	v_cndmask_b32_e64 v201, v181, 0, vcc
	v_pk_add_f32 v[144:145], v[86:87], v[144:145]
	v_cndmask_b32_e64 v200, v184, 0, vcc
	v_mul_f32_e32 v154, 0x3d372713, v144
	v_mul_f32_e32 v155, 0x3d372713, v145
	v_mul_f32_e32 v154, v144, v154
	v_mul_f32_e32 v155, v145, v155
	v_fma_f32 v154, v144, v154, v144
	v_fma_f32 v155, v145, v155, v145
	v_pk_fma_f32 v[152:153], v[76:77], v[200:201], v[152:153]
	v_mul_f32_e32 v154, 0xc0135761, v154
	v_mul_f32_e32 v155, 0xc0135761, v155
	v_pk_fma_f32 v[152:153], v[80:81], v[198:199], v[152:153]
	v_exp_f32_e32 v154, v154
	v_exp_f32_e32 v155, v155
	v_pk_add_f32 v[152:153], v[84:85], v[152:153]
	v_cndmask_b32_e64 v196, v196, 0, s[48:49]
	v_mul_f32_e32 v198, 0x3d372713, v152
	v_mul_f32_e32 v199, 0x3d372713, v153
	v_mul_f32_e32 v198, v152, v198
; __device__ __forceinline__ unsigned pk2(float lo, float hi) { const f32x2_cv v = {lo, hi}; const bf16x2_cv b = __builtin_convertvector(v, bf16x2_cv); return __builtin_bit_cast(unsigned, b); }
; __device__ __forceinline__ float dpp_ror1(float v) { return __builtin_bit_cast(float, __builtin_amdgcn_update_dpp(0, __builtin_bit_cast(int, v), 0x121, 0xF, 0xF, false)); }
; __device__ __forceinline__ float dpp_rol1(float v) { return __builtin_bit_cast(float, __builtin_amdgcn_update_dpp(0, __builtin_bit_cast(int, v), 0x12F, 0xF, 0xF, false)); }
;     __device__ __forceinline__ void operator()(const pg8::f32x4 (&acc)[2][2][4][2], const pg8::Unit& u, int wr, int wc, int fr, int fq) const {
;     ...
;                     const float ruC = dpp_ror1(x0), rdN = m < 3 ? dpp_rol1(acc[ai][0][m < 3 ? m + 1 : 3][n][e]) : 0.f;
;                     float xu = fr == 0 ? ruP[c] : ruC, xd = fr == 15 ? rdN : rdC[c];
;                     xu = first ? 0.f : xu; xd = last ? 0.f : xd;
;                     ruP[c] = ruC; rdC[c] = rdN;
;                     const float x = w0[c] * xu + w1[c] * x0 + w2[c] * xd + bb[c];
;                     const float u2 = -2.302208198f * (x + 0.044715f * x * x * x);
;                     res[c] = x * __builtin_amdgcn_rcpf(1.0f + __builtin_amdgcn_exp2f(u2)) * acc[ai][1][m][n][e];
;                 }
;                 if (rl >= 1 && rl <= 62 && gr < nrows) { v4u o; o.x = pk2(res[0], res[1]); o.y = pk2(res[2], res[3]); o.z = pk2(res[4], res[5]); o.w = pk2(res[6], res[7]);
;                     *(v4u*)(G + (size_t)gr * DFF + ch0) = o; }
	v_mul_f32_e32 v199, v153, v199
	v_fma_f32 v198, v152, v198, v152
	v_fma_f32 v199, v153, v199, v153
	v_add_f32_e32 v154, 1.0, v154
	v_add_f32_e32 v155, 1.0, v155
	v_mul_f32_e32 v198, 0xc0135761, v198
	v_mul_f32_e32 v199, 0xc0135761, v199
	v_rcp_f32_e32 v154, v154
	v_rcp_f32_e32 v155, v155
	v_exp_f32_e32 v198, v198
	v_exp_f32_e32 v199, v199
	v_pk_mul_f32 v[144:145], v[144:145], v[154:155]
	v_add_f32_e32 v154, 1.0, v198
	v_add_f32_e32 v155, 1.0, v199
	v_cndmask_b32_e64 v199, v182, 0, vcc
	v_cndmask_b32_e64 v198, v195, 0, vcc
	v_pk_fma_f32 v[158:159], v[58:59], v[198:199], v[158:159]
	v_rcp_f32_e32 v154, v154
	v_pk_fma_f32 v[158:159], v[62:63], v[196:197], v[158:159]
	v_rcp_f32_e32 v155, v155
	v_pk_add_f32 v[158:159], v[66:67], v[158:159]
	v_pk_mul_f32 v[150:151], v[150:151], v[144:145]
	v_mul_f32_e32 v196, 0x3d372713, v158
	v_mul_f32_e32 v197, 0x3d372713, v159
	v_mul_f32_e32 v196, v158, v196
	v_mul_f32_e32 v197, v159, v197
	v_fma_f32 v196, v158, v196, v158
	v_fma_f32 v197, v159, v197, v159
	v_mul_f32_e32 v196, 0xc0135761, v196
	v_mul_f32_e32 v197, 0xc0135761, v197
	v_exp_f32_e32 v196, v196
	v_exp_f32_e32 v197, v197
	v_pk_mul_f32 v[144:145], v[152:153], v[154:155]
	v_add_f32_e32 v196, 1.0, v196
	v_add_f32_e32 v197, 1.0, v197
	v_rcp_f32_e32 v196, v196
	v_rcp_f32_e32 v197, v197
	v_pk_mul_f32 v[144:145], v[148:149], v[144:145]
	v_pk_mul_f32 v[148:149], v[158:159], v[196:197]
	s_nop 0
	v_pk_mul_f32 v[148:149], v[146:147], v[148:149]
	v_cvt_pk_bf16_f32 v144, v144, v145
	v_cvt_pk_bf16_f32 v147, v148, v149
	v_mov_b64_e32 v[148:149], s[6:7]
	v_mad_i64_i32 v[148:149], s[48:49], v194, s1, v[148:149]
	v_cvt_pk_bf16_f32 v145, v150, v151
	v_cvt_pk_bf16_f32 v146, v156, v157
	v_lshl_add_u64 v[148:149], v[170:171], 1, v[148:149]
	global_store_dwordx4 v[148:149], v[144:147], off
.LBB0_1086:
	s_or_b64 exec, exec, s[52:53]
	v_add_u32_e32 v194, s73, v174
	v_mov_b32_dpp v149, v140 row_ror:1 row_mask:0xf bank_mask:0xf
	v_mov_b32_dpp v148, v124 row_ror:15 row_mask:0xf bank_mask:0xf
	v_mov_b32_dpp v146, v141 row_ror:1 row_mask:0xf bank_mask:0xf
	v_mov_b32_dpp v144, v125 row_ror:15 row_mask:0xf bank_mask:0xf
	v_mov_b32_dpp v153, v142 row_ror:1 row_mask:0xf bank_mask:0xf
	v_mov_b32_dpp v152, v126 row_ror:15 row_mask:0xf bank_mask:0xf
	v_mov_b32_dpp v151, v143 row_ror:1 row_mask:0xf bank_mask:0xf
	v_mov_b32_dpp v150, v127 row_ror:15 row_mask:0xf bank_mask:0xf
	v_mov_b32_dpp v157, v136 row_ror:1 row_mask:0xf bank_mask:0xf
	v_mov_b32_dpp v156, v120 row_ror:15 row_mask:0xf bank_mask:0xf
	v_mov_b32_dpp v155, v137 row_ror:1 row_mask:0xf bank_mask:0xf
	v_mov_b32_dpp v154, v121 row_ror:15 row_mask:0xf bank_mask:0xf
	v_mov_b32_dpp v159, v138 row_ror:1 row_mask:0xf bank_mask:0xf
	v_mov_b32_dpp v158, v122 row_ror:15 row_mask:0xf bank_mask:0xf
	v_mov_b32_dpp v147, v139 row_ror:1 row_mask:0xf bank_mask:0xf
	v_mov_b32_dpp v145, v123 row_ror:15 row_mask:0xf bank_mask:0xf
	v_cmp_gt_i32_e32 vcc, s86, v194
	s_and_saveexec_b64 s[80:81], vcc
	s_cbranch_execz .LBB0_1088
	v_and_b32_e32 v200, 0x1fff, v194
	v_and_b32_e32 v201, 0xff, v194
	v_cmp_gt_i32_e64 s[48:49], s97, v194
	v_cndmask_b32_e64 v195, v159, v195, s[38:39]
	v_mov_b32_e32 v198, v138
	v_cndmask_b32_e64 v196, v201, v200, s[48:49]
	v_cmp_eq_u32_e32 vcc, 0, v196
	s_waitcnt vmcnt(0)
	v_mov_b32_e32 v199, v58
	v_mov_b32_e32 v196, v70
	v_cndmask_b32_e64 v197, v195, 0, vcc
	v_cmp_eq_u32_e64 s[52:53], s78, v200
	v_pk_mul_f32 v[196:197], v[198:199], v[196:197]
	v_cndmask_b32_e64 v193, v193, v158, s[40:41]
	v_cndmask_b32_e64 v195, 0, 1, s[52:53]
	v_cmp_eq_u32_e64 s[52:53], s12, v201
	v_add_f32_e32 v138, v196, v197
	v_cndmask_b32_e64 v192, v157, v192, s[38:39]
	v_cndmask_b32_e64 v196, 0, 1, s[52:53]
	v_cndmask_b32_e64 v195, v196, v195, s[48:49]
	v_and_b32_e32 v195, 1, v195
	v_cmp_eq_u32_e64 s[48:49], 1, v195
	v_mov_b32_e32 v196, v136
	v_mov_b32_e32 v197, v56
	v_cndmask_b32_e64 v193, v193, 0, s[48:49]
	v_fmac_f32_e32 v138, v62, v193
	v_add_f32_e32 v138, v66, v138
	v_mul_f32_e32 v193, 0x3d372713, v138
	v_mul_f32_e32 v193, v138, v193
	v_fma_f32 v193, v138, v193, v138
	v_mul_f32_e32 v193, 0xc0135761, v193
	v_exp_f32_e32 v195, v193
	v_cndmask_b32_e64 v193, v192, 0, vcc
	v_mov_b32_e32 v192, v68
	v_pk_mul_f32 v[192:193], v[196:197], v[192:193]
	v_cndmask_b32_e64 v191, v191, v156, s[40:41]
	v_add_f32_e32 v136, v192, v193
	v_cndmask_b32_e64 v191, v191, 0, s[48:49]
	v_fmac_f32_e32 v136, v60, v191
	v_add_f32_e32 v136, v64, v136
	v_mul_f32_e32 v191, 0x3d372713, v136
	v_mul_f32_e32 v191, v136, v191
	v_fma_f32 v191, v136, v191, v136
	v_mul_f32_e32 v191, 0xc0135761, v191
	v_exp_f32_e32 v191, v191
	v_add_f32_e32 v192, 1.0, v195
	v_rcp_f32_e32 v192, v192
	v_add_f32_e32 v191, 1.0, v191
	v_rcp_f32_e32 v191, v191
	v_mul_f32_e32 v138, v138, v192
	v_mul_f32_e32 v138, v130, v138
	v_mul_f32_e32 v130, v136, v191
	v_cndmask_b32_e64 v136, v155, v190, s[38:39]
	v_cndmask_b32_e64 v191, v136, 0, vcc
	v_mov_b32_e32 v136, v137
	v_mov_b32_e32 v137, v57
	v_mov_b32_e32 v190, v69
	v_pk_mul_f32 v[136:137], v[136:137], v[190:191]
	v_mul_f32_e32 v130, v128, v130
	v_add_f32_e32 v136, v136, v137
	v_cndmask_b32_e64 v137, v189, v154, s[40:41]
	v_cndmask_b32_e64 v137, v137, 0, s[48:49]
	v_fmac_f32_e32 v136, v61, v137
	v_add_f32_e32 v190, v65, v136
	v_mul_f32_e32 v136, 0x3d372713, v190
	v_mul_f32_e32 v136, v190, v136
	v_fma_f32 v136, v190, v136, v190
	v_mul_f32_e32 v136, 0xc0135761, v136
	v_exp_f32_e32 v191, v136
	v_cndmask_b32_e64 v136, v153, v188, s[38:39]
	v_cndmask_b32_e64 v137, v136, 0, vcc
	v_mov_b32_e32 v188, v142
	v_mov_b32_e32 v189, v78
	v_mov_b32_e32 v136, v94
	v_pk_mul_f32 v[136:137], v[188:189], v[136:137]
	v_mov_b32_e32 v142, v143
	v_add_f32_e32 v136, v136, v137
; __device__ __forceinline__ unsigned pk2(float lo, float hi) { const f32x2_cv v = {lo, hi}; const bf16x2_cv b = __builtin_convertvector(v, bf16x2_cv); return __builtin_bit_cast(unsigned, b); }
; __device__ __forceinline__ float dpp_ror1(float v) { return __builtin_bit_cast(float, __builtin_amdgcn_update_dpp(0, __builtin_bit_cast(int, v), 0x121, 0xF, 0xF, false)); }
; __device__ __forceinline__ float dpp_rol1(float v) { return __builtin_bit_cast(float, __builtin_amdgcn_update_dpp(0, __builtin_bit_cast(int, v), 0x12F, 0xF, 0xF, false)); }
;     __device__ __forceinline__ void operator()(const pg8::f32x4 (&acc)[2][2][4][2], const pg8::Unit& u, int wr, int wc, int fr, int fq) const {
;     ...
;                     const float ruC = dpp_ror1(x0), rdN = m < 3 ? dpp_rol1(acc[ai][0][m < 3 ? m + 1 : 3][n][e]) : 0.f;
;                     float xu = fr == 0 ? ruP[c] : ruC, xd = fr == 15 ? rdN : rdC[c];
;                     xu = first ? 0.f : xu; xd = last ? 0.f : xd;
;                     ruP[c] = ruC; rdC[c] = rdN;
;                     const float x = w0[c] * xu + w1[c] * x0 + w2[c] * xd + bb[c];
;                     const float u2 = -2.302208198f * (x + 0.044715f * x * x * x);
;                     res[c] = x * __builtin_amdgcn_rcpf(1.0f + __builtin_amdgcn_exp2f(u2)) * acc[ai][1][m][n][e];
;                 }
;                 if (rl >= 1 && rl <= 62 && gr < nrows) { v4u o; o.x = pk2(res[0], res[1]); o.y = pk2(res[2], res[3]); o.z = pk2(res[4], res[5]); o.w = pk2(res[6], res[7]);
;                     *(v4u*)(G + (size_t)gr * DFF + ch0) = o; }
	v_cndmask_b32_e64 v137, v187, v152, s[40:41]
	v_cndmask_b32_e64 v137, v137, 0, s[48:49]
	v_fmac_f32_e32 v136, v82, v137
	v_add_f32_e32 v187, v86, v136
	v_mul_f32_e32 v136, 0x3d372713, v187
	v_mul_f32_e32 v136, v187, v136
	v_fma_f32 v136, v187, v136, v187
	v_mul_f32_e32 v136, 0xc0135761, v136
	v_exp_f32_e32 v136, v136
	v_mov_b32_e32 v143, v79
	v_add_f32_e32 v128, 1.0, v191
	v_rcp_f32_e32 v128, v128
	v_add_f32_e32 v136, 1.0, v136
	v_rcp_f32_e32 v188, v136
	v_cndmask_b32_e64 v136, v151, v186, s[38:39]
	v_cndmask_b32_e64 v137, v136, 0, vcc
	v_mov_b32_e32 v136, v95
	v_pk_mul_f32 v[136:137], v[142:143], v[136:137]
	v_mul_f32_e32 v128, v190, v128
	v_add_f32_e32 v136, v136, v137
	v_cndmask_b32_e64 v137, v185, v150, s[40:41]
	v_cndmask_b32_e64 v137, v137, 0, s[48:49]
	v_fmac_f32_e32 v136, v83, v137
	v_add_f32_e32 v142, v87, v136
	v_mul_f32_e32 v136, 0x3d372713, v142
	v_mul_f32_e32 v136, v142, v136
	v_fma_f32 v136, v142, v136, v142
	v_mul_f32_e32 v136, 0xc0135761, v136
	v_exp_f32_e32 v136, v136
	v_mul_f32_e32 v143, v129, v128
	v_mov_b32_e32 v137, v76
	v_mul_f32_e32 v185, v187, v188
	v_add_f32_e32 v128, 1.0, v136
	v_rcp_f32_e32 v186, v128
	v_cndmask_b32_e64 v128, v149, v184, s[38:39]
	v_cndmask_b32_e64 v129, v128, 0, vcc
	v_mov_b32_e32 v136, v140
	v_mov_b32_e32 v128, v92
	v_pk_mul_f32 v[128:129], v[136:137], v[128:129]
	v_mul_f32_e32 v137, v134, v185
	v_add_f32_e32 v128, v128, v129
	v_cndmask_b32_e64 v129, v183, v148, s[40:41]
	v_cndmask_b32_e64 v129, v129, 0, s[48:49]
	v_fmac_f32_e32 v128, v80, v129
	v_add_f32_e32 v136, v84, v128
	v_mul_f32_e32 v128, 0x3d372713, v136
	v_mul_f32_e32 v128, v136, v128
	v_fma_f32 v128, v136, v128, v136
	v_mul_f32_e32 v128, 0xc0135761, v128
	v_exp_f32_e32 v128, v128
	v_mul_f32_e32 v129, v142, v186
	v_mul_f32_e32 v140, v135, v129
	v_mov_b32_e32 v134, v141
	v_add_f32_e32 v128, 1.0, v128
	v_rcp_f32_e32 v142, v128
	v_cndmask_b32_e64 v128, v146, v181, s[38:39]
	v_cndmask_b32_e64 v129, v128, 0, vcc
	v_mov_b32_e32 v135, v77
	v_mov_b32_e32 v128, v93
	v_pk_mul_f32 v[128:129], v[134:135], v[128:129]
	v_mov_b32_e32 v134, v139
	v_add_f32_e32 v128, v128, v129
	v_cndmask_b32_e64 v129, v179, v144, s[40:41]
	v_cndmask_b32_e64 v129, v129, 0, s[48:49]
	v_fmac_f32_e32 v128, v81, v129
	v_add_f32_e32 v141, v85, v128
	v_mul_f32_e32 v128, 0x3d372713, v141
	v_mul_f32_e32 v128, v141, v128
	v_fma_f32 v128, v141, v128, v141
	v_mul_f32_e32 v128, 0xc0135761, v128
	v_exp_f32_e32 v179, v128
	v_cndmask_b32_e64 v128, v147, v182, s[38:39]
	v_cndmask_b32_e64 v129, v128, 0, vcc
	v_mov_b32_e32 v135, v59
	v_mov_b32_e32 v128, v71
	v_pk_mul_f32 v[128:129], v[134:135], v[128:129]
	v_add_f32_e32 v135, 1.0, v179
	v_add_f32_e32 v128, v128, v129
	v_cndmask_b32_e64 v129, v180, v145, s[40:41]
	v_cndmask_b32_e64 v129, v129, 0, s[48:49]
	v_fmac_f32_e32 v128, v63, v129
	v_add_f32_e32 v128, v67, v128
	v_mul_f32_e32 v129, 0x3d372713, v128
	v_mul_f32_e32 v129, v128, v129
	v_fma_f32 v129, v128, v129, v128
	v_mul_f32_e32 v129, 0xc0135761, v129
	v_exp_f32_e32 v129, v129
	v_rcp_f32_e32 v135, v135
	v_mul_f32_e32 v134, v136, v142
	v_mul_f32_e32 v132, v132, v134
	v_add_f32_e32 v129, 1.0, v129
	v_rcp_f32_e32 v129, v129
	v_mul_f32_e32 v134, v141, v135
	v_mul_f32_e32 v133, v133, v134
	v_cvt_pk_bf16_f32 v130, v130, v143
	v_mul_f32_e32 v128, v128, v129
	v_mul_f32_e32 v131, v131, v128
	v_cvt_pk_bf16_f32 v128, v132, v133
	v_mov_b64_e32 v[132:133], s[6:7]
	v_mad_i64_i32 v[132:133], s[48:49], v194, s1, v[132:133]
	v_cvt_pk_bf16_f32 v129, v137, v140
	v_cvt_pk_bf16_f32 v131, v138, v131
	v_lshl_add_u64 v[132:133], v[170:171], 1, v[132:133]
	global_store_dwordx4 v[132:133], v[128:131], off
.LBB0_1088:
	s_or_b64 exec, exec, s[80:81]
	v_add_u32_e32 v179, s73, v175
	v_mov_b32_dpp v142, v124 row_ror:1 row_mask:0xf bank_mask:0xf
	v_mov_b32_dpp v140, v108 row_ror:15 row_mask:0xf bank_mask:0xf
	v_mov_b32_dpp v143, v125 row_ror:1 row_mask:0xf bank_mask:0xf
	v_mov_b32_dpp v141, v109 row_ror:15 row_mask:0xf bank_mask:0xf
	v_mov_b32_dpp v138, v126 row_ror:1 row_mask:0xf bank_mask:0xf
	v_mov_b32_dpp v136, v110 row_ror:15 row_mask:0xf bank_mask:0xf
	v_mov_b32_dpp v139, v127 row_ror:1 row_mask:0xf bank_mask:0xf
	v_mov_b32_dpp v137, v111 row_ror:15 row_mask:0xf bank_mask:0xf
	v_mov_b32_dpp v134, v120 row_ror:1 row_mask:0xf bank_mask:0xf
	v_mov_b32_dpp v132, v104 row_ror:15 row_mask:0xf bank_mask:0xf
	v_mov_b32_dpp v135, v121 row_ror:1 row_mask:0xf bank_mask:0xf
	v_mov_b32_dpp v133, v105 row_ror:15 row_mask:0xf bank_mask:0xf
	v_mov_b32_dpp v130, v122 row_ror:1 row_mask:0xf bank_mask:0xf
	v_mov_b32_dpp v128, v106 row_ror:15 row_mask:0xf bank_mask:0xf
	v_mov_b32_dpp v131, v123 row_ror:1 row_mask:0xf bank_mask:0xf
	v_mov_b32_dpp v129, v107 row_ror:15 row_mask:0xf bank_mask:0xf
	v_cmp_gt_i32_e32 vcc, s86, v179
	s_and_saveexec_b64 s[80:81], vcc
	v_readlane_b32 s79, v254, 48
	v_readlane_b32 s83, v254, 49
	s_cbranch_execz .LBB0_1090
; __device__ __forceinline__ float dpp_ror1(float v) { return __builtin_bit_cast(float, __builtin_amdgcn_update_dpp(0, __builtin_bit_cast(int, v), 0x121, 0xF, 0xF, false)); }
; __device__ __forceinline__ float dpp_rol1(float v) { return __builtin_bit_cast(float, __builtin_amdgcn_update_dpp(0, __builtin_bit_cast(int, v), 0x12F, 0xF, 0xF, false)); }
;     __device__ __forceinline__ void operator()(const pg8::f32x4 (&acc)[2][2][4][2], const pg8::Unit& u, int wr, int wc, int fr, int fq) const {
;     ...
;                 bool first, last; if (gr < ML) { const int t = gr & 8191; first = t == 0; last = t == 8191; } else { const int t = (gr - ML) & 255; first = t == 0; last = t == 255; }
;                 float res[8];
; #pragma unroll
;                 for (int c = 0; c < 8; ++c) {
;                     const int n = c >> 2, e = c & 3;
;                     const float x0 = acc[ai][0][m][n][e];
;                     const float ruC = dpp_ror1(x0), rdN = m < 3 ? dpp_rol1(acc[ai][0][m < 3 ? m + 1 : 3][n][e]) : 0.f;
;                     float xu = fr == 0 ? ruP[c] : ruC, xd = fr == 15 ? rdN : rdC[c];
;                     xu = first ? 0.f : xu; xd = last ? 0.f : xd;
;                     ruP[c] = ruC; rdC[c] = rdN;
;                     const float x = w0[c] * xu + w1[c] * x0 + w2[c] * xd + bb[c];
;                     const float u2 = -2.302208198f * (x + 0.044715f * x * x * x);
;                     res[c] = x * __builtin_amdgcn_rcpf(1.0f + __builtin_amdgcn_exp2f(u2)) * acc[ai][1][m][n][e];
	v_and_b32_e32 v184, 0x1fff, v179
	v_and_b32_e32 v185, 0xff, v179
	v_cmp_gt_i32_e64 s[48:49], s97, v179
	v_cndmask_b32_e64 v159, v130, v159, s[38:39]
	v_mov_b32_e32 v182, v122
	v_cndmask_b32_e64 v180, v185, v184, s[48:49]
	v_cmp_eq_u32_e32 vcc, 0, v180
	s_waitcnt vmcnt(0)
	v_mov_b32_e32 v183, v58
	v_mov_b32_e32 v180, v70
	v_cndmask_b32_e64 v181, v159, 0, vcc
	v_cmp_eq_u32_e64 s[52:53], s78, v184
	v_pk_mul_f32 v[180:181], v[182:183], v[180:181]
	v_cndmask_b32_e64 v158, v158, v128, s[40:41]
	v_cndmask_b32_e64 v159, 0, 1, s[52:53]
	v_cmp_eq_u32_e64 s[52:53], s12, v185
	v_add_f32_e32 v122, v180, v181
	v_cndmask_b32_e64 v157, v134, v157, s[38:39]
	v_cndmask_b32_e64 v180, 0, 1, s[52:53]
	v_cndmask_b32_e64 v159, v180, v159, s[48:49]
	v_and_b32_e32 v159, 1, v159
	v_cmp_eq_u32_e64 s[48:49], 1, v159
	v_cndmask_b32_e64 v159, v157, 0, vcc
	v_mov_b32_e32 v180, v120
	v_cndmask_b32_e64 v158, v158, 0, s[48:49]
	v_fmac_f32_e32 v122, v62, v158
	v_add_f32_e32 v122, v66, v122
	v_mul_f32_e32 v158, 0x3d372713, v122
	v_mul_f32_e32 v158, v122, v158
	v_fma_f32 v158, v122, v158, v122
	v_mul_f32_e32 v158, 0xc0135761, v158
	v_exp_f32_e32 v182, v158
	v_mov_b32_e32 v181, v56
	v_mov_b32_e32 v158, v68
	v_pk_mul_f32 v[158:159], v[180:181], v[158:159]
	v_cndmask_b32_e64 v156, v156, v132, s[40:41]
	v_add_f32_e32 v120, v158, v159
	v_cndmask_b32_e64 v156, v156, 0, s[48:49]
	v_fmac_f32_e32 v120, v60, v156
	v_add_f32_e32 v120, v64, v120
	v_mul_f32_e32 v156, 0x3d372713, v120
	v_mul_f32_e32 v156, v120, v156
	v_fma_f32 v156, v120, v156, v120
	v_mul_f32_e32 v156, 0xc0135761, v156
	v_exp_f32_e32 v156, v156
	v_add_f32_e32 v157, 1.0, v182
	v_rcp_f32_e32 v157, v157
	v_add_f32_e32 v156, 1.0, v156
	v_rcp_f32_e32 v156, v156
	v_mul_f32_e32 v122, v122, v157
	v_mul_f32_e32 v122, v114, v122
	v_mul_f32_e32 v114, v120, v156
	v_cndmask_b32_e64 v120, v135, v155, s[38:39]
	v_cndmask_b32_e64 v157, v120, 0, vcc
	v_mov_b32_e32 v120, v121
	v_mov_b32_e32 v121, v57
	v_mov_b32_e32 v156, v69
	v_pk_mul_f32 v[120:121], v[120:121], v[156:157]
	v_mov_b32_e32 v155, v78
	v_add_f32_e32 v120, v120, v121
	v_cndmask_b32_e64 v121, v154, v133, s[40:41]
	v_cndmask_b32_e64 v121, v121, 0, s[48:49]
	v_fmac_f32_e32 v120, v61, v121
	v_add_f32_e32 v156, v65, v120
	v_mul_f32_e32 v120, 0x3d372713, v156
	v_mul_f32_e32 v120, v156, v120
	v_fma_f32 v120, v156, v120, v156
	v_mul_f32_e32 v120, 0xc0135761, v120
	v_exp_f32_e32 v157, v120
	v_cndmask_b32_e64 v120, v138, v153, s[38:39]
	v_cndmask_b32_e64 v121, v120, 0, vcc
	v_mov_b32_e32 v154, v126
	v_mov_b32_e32 v120, v94
	v_pk_mul_f32 v[120:121], v[154:155], v[120:121]
	v_mov_b32_e32 v126, v127
	v_add_f32_e32 v120, v120, v121
	v_cndmask_b32_e64 v121, v152, v136, s[40:41]
	v_cndmask_b32_e64 v121, v121, 0, s[48:49]
	v_fmac_f32_e32 v120, v82, v121
	v_add_f32_e32 v152, v86, v120
	v_mul_f32_e32 v120, 0x3d372713, v152
	v_mul_f32_e32 v120, v152, v120
	v_fma_f32 v120, v152, v120, v152
	v_mul_f32_e32 v120, 0xc0135761, v120
	v_exp_f32_e32 v120, v120
	v_mov_b32_e32 v127, v79
	v_mul_f32_e32 v114, v112, v114
	v_add_f32_e32 v112, 1.0, v157
	v_add_f32_e32 v120, 1.0, v120
	v_rcp_f32_e32 v153, v120
	v_cndmask_b32_e64 v120, v139, v151, s[38:39]
	v_cndmask_b32_e64 v121, v120, 0, vcc
	v_mov_b32_e32 v120, v95
	v_pk_mul_f32 v[120:121], v[126:127], v[120:121]
	v_rcp_f32_e32 v112, v112
	v_add_f32_e32 v120, v120, v121
	v_cndmask_b32_e64 v121, v150, v137, s[40:41]
	v_cndmask_b32_e64 v121, v121, 0, s[48:49]
	v_fmac_f32_e32 v120, v83, v121
	v_add_f32_e32 v126, v87, v120
	v_mul_f32_e32 v120, 0x3d372713, v126
	v_mul_f32_e32 v120, v126, v120
	v_fma_f32 v120, v126, v120, v126
	v_mul_f32_e32 v120, 0xc0135761, v120
	v_exp_f32_e32 v120, v120
	v_mul_f32_e32 v112, v156, v112
	v_mul_f32_e32 v127, v113, v112
	v_mov_b32_e32 v121, v76
	v_add_f32_e32 v112, 1.0, v120
	v_rcp_f32_e32 v151, v112
	v_cndmask_b32_e64 v112, v142, v149, s[38:39]
	v_cndmask_b32_e64 v113, v112, 0, vcc
	v_mov_b32_e32 v120, v124
	v_mov_b32_e32 v112, v92
	v_pk_mul_f32 v[112:113], v[120:121], v[112:113]
	v_mul_f32_e32 v150, v152, v153
	v_add_f32_e32 v112, v112, v113
	v_cndmask_b32_e64 v113, v148, v140, s[40:41]
	v_cndmask_b32_e64 v113, v113, 0, s[48:49]
	v_fmac_f32_e32 v112, v80, v113
	v_add_f32_e32 v120, v84, v112
	v_mul_f32_e32 v112, 0x3d372713, v120
	v_mul_f32_e32 v112, v120, v112
	v_fma_f32 v112, v120, v112, v120
	v_mul_f32_e32 v112, 0xc0135761, v112
	v_exp_f32_e32 v112, v112
	v_mul_f32_e32 v113, v126, v151
	v_mul_f32_e32 v121, v118, v150
	v_mul_f32_e32 v124, v119, v113
	v_add_f32_e32 v112, 1.0, v112
	v_rcp_f32_e32 v126, v112
	v_cndmask_b32_e64 v112, v143, v146, s[38:39]
	v_cndmask_b32_e64 v113, v112, 0, vcc
	v_mov_b32_e32 v118, v125
	v_mov_b32_e32 v119, v77
	v_mov_b32_e32 v112, v93
	v_pk_mul_f32 v[112:113], v[118:119], v[112:113]
	v_mov_b32_e32 v118, v123
	v_add_f32_e32 v112, v112, v113
	v_cndmask_b32_e64 v113, v144, v141, s[40:41]
	v_cndmask_b32_e64 v113, v113, 0, s[48:49]
	v_fmac_f32_e32 v112, v81, v113
	v_add_f32_e32 v125, v85, v112
	v_mul_f32_e32 v112, 0x3d372713, v125
	v_mul_f32_e32 v112, v125, v112
	v_fma_f32 v112, v125, v112, v125
	v_mul_f32_e32 v112, 0xc0135761, v112
	v_exp_f32_e32 v144, v112
	v_cndmask_b32_e64 v112, v131, v147, s[38:39]
	v_cndmask_b32_e64 v113, v112, 0, vcc
	v_mov_b32_e32 v119, v59
	v_mov_b32_e32 v112, v71
	v_pk_mul_f32 v[112:113], v[118:119], v[112:113]
	v_add_f32_e32 v119, 1.0, v144
	v_add_f32_e32 v112, v112, v113
	v_cndmask_b32_e64 v113, v145, v129, s[40:41]
	v_cndmask_b32_e64 v113, v113, 0, s[48:49]
	v_fmac_f32_e32 v112, v63, v113
	v_add_f32_e32 v112, v67, v112
	v_mul_f32_e32 v113, 0x3d372713, v112
	v_mul_f32_e32 v113, v112, v113
	v_fma_f32 v113, v112, v113, v112
	v_mul_f32_e32 v113, 0xc0135761, v113
	v_exp_f32_e32 v113, v113
	v_rcp_f32_e32 v119, v119
	v_mul_f32_e32 v118, v120, v126
	v_mul_f32_e32 v116, v116, v118
	v_add_f32_e32 v113, 1.0, v113
	v_rcp_f32_e32 v113, v113
	v_mul_f32_e32 v118, v125, v119
	v_mul_f32_e32 v117, v117, v118
	v_cvt_pk_bf16_f32 v114, v114, v127
	v_mul_f32_e32 v112, v112, v113
	v_mul_f32_e32 v115, v115, v112
	v_cvt_pk_bf16_f32 v112, v116, v117
	v_mov_b64_e32 v[116:117], s[6:7]
	v_mad_i64_i32 v[116:117], s[48:49], v179, s1, v[116:117]
	v_cvt_pk_bf16_f32 v113, v121, v124
	v_cvt_pk_bf16_f32 v115, v122, v115
	v_lshl_add_u64 v[116:117], v[170:171], 1, v[116:117]
	global_store_dwordx4 v[116:117], v[112:115], off
; __device__ __forceinline__ unsigned pk2(float lo, float hi) { const f32x2_cv v = {lo, hi}; const bf16x2_cv b = __builtin_convertvector(v, bf16x2_cv); return __builtin_bit_cast(unsigned, b); }
; __device__ __forceinline__ float dpp_ror1(float v) { return __builtin_bit_cast(float, __builtin_amdgcn_update_dpp(0, __builtin_bit_cast(int, v), 0x121, 0xF, 0xF, false)); }
; __device__ __forceinline__ float dpp_rol1(float v) { return __builtin_bit_cast(float, __builtin_amdgcn_update_dpp(0, __builtin_bit_cast(int, v), 0x12F, 0xF, 0xF, false)); }
;     __device__ __forceinline__ void operator()(const pg8::f32x4 (&acc)[2][2][4][2], const pg8::Unit& u, int wr, int wc, int fr, int fq) const {
;     ...
;                     const float ruC = dpp_ror1(x0), rdN = m < 3 ? dpp_rol1(acc[ai][0][m < 3 ? m + 1 : 3][n][e]) : 0.f;
;                     float xu = fr == 0 ? ruP[c] : ruC, xd = fr == 15 ? rdN : rdC[c];
;                     xu = first ? 0.f : xu; xd = last ? 0.f : xd;
;                     ruP[c] = ruC; rdC[c] = rdN;
;                     const float x = w0[c] * xu + w1[c] * x0 + w2[c] * xd + bb[c];
;                     const float u2 = -2.302208198f * (x + 0.044715f * x * x * x);
;                     res[c] = x * __builtin_amdgcn_rcpf(1.0f + __builtin_amdgcn_exp2f(u2)) * acc[ai][1][m][n][e];
;                 }
;                 if (rl >= 1 && rl <= 62 && gr < nrows) { v4u o; o.x = pk2(res[0], res[1]); o.y = pk2(res[2], res[3]); o.z = pk2(res[4], res[5]); o.w = pk2(res[6], res[7]);
;                     *(v4u*)(G + (size_t)gr * DFF + ch0) = o; }
.LBB0_1090:
	s_or_b64 exec, exec, s[80:81]
	s_nop 0
	v_add_u32_e32 v112, s73, v176
	v_cmp_gt_i32_e32 vcc, s86, v112
	v_mov_b32_dpp v119, v108 row_ror:1 row_mask:0xf bank_mask:0xf
	v_mov_b32_dpp v120, v109 row_ror:1 row_mask:0xf bank_mask:0xf
	v_mov_b32_dpp v117, v110 row_ror:1 row_mask:0xf bank_mask:0xf
	v_mov_b32_dpp v118, v111 row_ror:1 row_mask:0xf bank_mask:0xf
	v_mov_b32_dpp v115, v104 row_ror:1 row_mask:0xf bank_mask:0xf
	v_mov_b32_dpp v116, v105 row_ror:1 row_mask:0xf bank_mask:0xf
	v_mov_b32_dpp v113, v106 row_ror:1 row_mask:0xf bank_mask:0xf
	v_mov_b32_dpp v114, v107 row_ror:1 row_mask:0xf bank_mask:0xf
	s_and_b64 s[48:49], s[44:45], vcc
	s_and_saveexec_b64 s[52:53], s[48:49]
	s_cbranch_execz .LBB0_1092
	v_and_b32_e32 v121, 0x1fff, v112
	v_and_b32_e32 v122, 0xff, v112
	v_cmp_gt_i32_e32 vcc, s97, v112
	v_cmp_eq_u32_e64 s[48:49], s78, v121
	v_cndmask_b32_e64 v119, v119, v142, s[38:39]
	v_cndmask_b32_e32 v123, v122, v121, vcc
	v_cndmask_b32_e64 v121, 0, 1, s[48:49]
	v_cmp_eq_u32_e64 s[48:49], s12, v122
	v_cndmask_b32_e64 v120, v120, v143, s[38:39]
	s_waitcnt vmcnt(0)
	v_pk_mul_f32 v[108:109], v[108:109], v[92:93]
	v_cndmask_b32_e64 v122, 0, 1, s[48:49]
	v_cndmask_b32_e32 v121, v122, v121, vcc
	v_and_b32_e32 v122, 1, v121
	v_cmp_eq_u32_e64 s[48:49], 0, v123
	v_cmp_eq_u32_e32 vcc, 1, v122
	v_cndmask_b32_e64 v117, v117, v138, s[38:39]
	v_cndmask_b32_e64 v121, v120, 0, s[48:49]
	v_cndmask_b32_e64 v120, v119, 0, s[48:49]
	v_pk_fma_f32 v[108:109], v[76:77], v[120:121], v[108:109]
	v_cndmask_b32_e64 v121, v141, 0, vcc
	v_cndmask_b32_e64 v120, v140, 0, vcc
	v_pk_fma_f32 v[108:109], v[80:81], v[120:121], v[108:109]
	v_cndmask_b32_e64 v118, v118, v139, s[38:39]
	v_pk_add_f32 v[108:109], v[84:85], v[108:109]
	v_pk_mul_f32 v[110:111], v[110:111], v[94:95]
	v_mul_f32_e32 v119, 0x3d372713, v108
	v_mul_f32_e32 v119, v108, v119
	v_fma_f32 v119, v108, v119, v108
	v_mul_f32_e32 v119, 0xc0135761, v119
	v_exp_f32_e32 v119, v119
	v_mul_f32_e32 v120, 0x3d372713, v109
	v_mul_f32_e32 v120, v109, v120
	v_fma_f32 v120, v109, v120, v109
	v_mul_f32_e32 v120, 0xc0135761, v120
	v_add_f32_e32 v119, 1.0, v119
	v_exp_f32_e32 v121, v120
	v_rcp_f32_e32 v120, v119
	v_cndmask_b32_e64 v119, v118, 0, s[48:49]
	v_cndmask_b32_e64 v118, v117, 0, s[48:49]
	v_pk_fma_f32 v[110:111], v[78:79], v[118:119], v[110:111]
	v_cndmask_b32_e64 v119, v137, 0, vcc
	v_cndmask_b32_e64 v118, v136, 0, vcc
	v_pk_fma_f32 v[110:111], v[82:83], v[118:119], v[110:111]
	v_add_f32_e32 v121, 1.0, v121
	v_pk_add_f32 v[110:111], v[86:87], v[110:111]
	v_rcp_f32_e32 v121, v121
	v_mul_f32_e32 v117, 0x3d372713, v110
	v_mul_f32_e32 v117, v110, v117
	v_mul_f32_e32 v118, 0x3d372713, v111
	v_fma_f32 v117, v110, v117, v110
	v_mul_f32_e32 v118, v111, v118
	v_mul_f32_e32 v117, 0xc0135761, v117
	v_fma_f32 v118, v111, v118, v111
	v_exp_f32_e32 v117, v117
	v_mul_f32_e32 v118, 0xc0135761, v118
	v_exp_f32_e32 v119, v118
	v_pk_mul_f32 v[108:109], v[108:109], v[120:121]
	v_add_f32_e32 v117, 1.0, v117
	v_rcp_f32_e32 v118, v117
	v_add_f32_e32 v117, 1.0, v119
	v_rcp_f32_e32 v119, v117
	v_pk_mul_f32 v[100:101], v[100:101], v[108:109]
	v_cndmask_b32_e64 v113, v113, v130, s[38:39]
	v_cndmask_b32_e64 v114, v114, v131, s[38:39]
	v_pk_mul_f32 v[108:109], v[110:111], v[118:119]
	v_cndmask_b32_e64 v110, v115, v134, s[38:39]
	v_cndmask_b32_e64 v111, v116, v135, s[38:39]
	v_pk_mul_f32 v[104:105], v[104:105], v[68:69]
	v_cndmask_b32_e64 v111, v111, 0, s[48:49]
	v_cndmask_b32_e64 v110, v110, 0, s[48:49]
	v_pk_mul_f32 v[106:107], v[106:107], v[70:71]
	v_cndmask_b32_e64 v115, v114, 0, s[48:49]
	v_cndmask_b32_e64 v114, v113, 0, s[48:49]
	v_pk_fma_f32 v[104:105], v[56:57], v[110:111], v[104:105]
	v_cndmask_b32_e64 v111, v133, 0, vcc
	v_cndmask_b32_e64 v110, v132, 0, vcc
	v_pk_fma_f32 v[106:107], v[58:59], v[114:115], v[106:107]
	v_cndmask_b32_e64 v115, v129, 0, vcc
	v_cndmask_b32_e64 v114, v128, 0, vcc
	v_pk_fma_f32 v[104:105], v[60:61], v[110:111], v[104:105]
	v_pk_fma_f32 v[106:107], v[62:63], v[114:115], v[106:107]
	v_pk_add_f32 v[104:105], v[64:65], v[104:105]
	v_pk_add_f32 v[106:107], v[66:67], v[106:107]
	v_mul_f32_e32 v110, 0x3d372713, v104
	v_mul_f32_e32 v111, 0x3d372713, v105
	v_mul_f32_e32 v113, 0x3d372713, v106
	v_mul_f32_e32 v110, v104, v110
	v_mul_f32_e32 v111, v105, v111
	v_mul_f32_e32 v113, v106, v113
	v_mul_f32_e32 v114, 0x3d372713, v107
	v_fma_f32 v110, v104, v110, v104
	v_fma_f32 v111, v105, v111, v105
	v_fma_f32 v113, v106, v113, v106
	v_mul_f32_e32 v114, v107, v114
	v_mul_f32_e32 v110, 0xc0135761, v110
	v_mul_f32_e32 v111, 0xc0135761, v111
	v_mul_f32_e32 v113, 0xc0135761, v113
	v_fma_f32 v114, v107, v114, v107
	v_exp_f32_e32 v110, v110
	v_exp_f32_e32 v111, v111
	v_exp_f32_e32 v113, v113
	v_mul_f32_e32 v114, 0xc0135761, v114
	v_exp_f32_e32 v115, v114
	v_add_f32_e32 v110, 1.0, v110
	v_add_f32_e32 v111, 1.0, v111
	v_add_f32_e32 v113, 1.0, v113
	v_rcp_f32_e32 v110, v110
	v_rcp_f32_e32 v111, v111
	v_rcp_f32_e32 v114, v113
	v_add_f32_e32 v113, 1.0, v115
	v_rcp_f32_e32 v115, v113
	v_pk_mul_f32 v[104:105], v[104:105], v[110:111]
	v_pk_mul_f32 v[102:103], v[102:103], v[108:109]
	v_pk_mul_f32 v[104:105], v[96:97], v[104:105]
	v_pk_mul_f32 v[96:97], v[106:107], v[114:115]
	s_nop 0
	v_pk_mul_f32 v[106:107], v[98:99], v[96:97]
	v_cvt_pk_bf16_f32 v96, v100, v101
	v_mov_b64_e32 v[100:101], s[6:7]
	v_mad_i64_i32 v[100:101], s[48:49], v112, s1, v[100:101]
	v_cvt_pk_bf16_f32 v97, v102, v103
	v_cvt_pk_bf16_f32 v98, v104, v105
	v_cvt_pk_bf16_f32 v99, v106, v107
	v_lshl_add_u64 v[100:101], v[170:171], 1, v[100:101]
	global_store_dwordx4 v[100:101], v[96:99], off
; __device__ __forceinline__ unsigned pk2(float lo, float hi) { const f32x2_cv v = {lo, hi}; const bf16x2_cv b = __builtin_convertvector(v, bf16x2_cv); return __builtin_bit_cast(unsigned, b); }
; __device__ __forceinline__ float dpp_ror1(float v) { return __builtin_bit_cast(float, __builtin_amdgcn_update_dpp(0, __builtin_bit_cast(int, v), 0x121, 0xF, 0xF, false)); }
; __device__ __forceinline__ float dpp_rol1(float v) { return __builtin_bit_cast(float, __builtin_amdgcn_update_dpp(0, __builtin_bit_cast(int, v), 0x12F, 0xF, 0xF, false)); }
;     __device__ __forceinline__ void operator()(const pg8::f32x4 (&acc)[2][2][4][2], const pg8::Unit& u, int wr, int wc, int fr, int fq) const {
;     ...
;                     const float ruC = dpp_ror1(x0), rdN = m < 3 ? dpp_rol1(acc[ai][0][m < 3 ? m + 1 : 3][n][e]) : 0.f;
;                     float xu = fr == 0 ? ruP[c] : ruC, xd = fr == 15 ? rdN : rdC[c];
;                     xu = first ? 0.f : xu; xd = last ? 0.f : xd;
;                     ruP[c] = ruC; rdC[c] = rdN;
;                     const float x = w0[c] * xu + w1[c] * x0 + w2[c] * xd + bb[c];
;                     const float u2 = -2.302208198f * (x + 0.044715f * x * x * x);
;                     res[c] = x * __builtin_amdgcn_rcpf(1.0f + __builtin_amdgcn_exp2f(u2)) * acc[ai][1][m][n][e];
;                 }
;                 if (rl >= 1 && rl <= 62 && gr < nrows) { v4u o; o.x = pk2(res[0], res[1]); o.y = pk2(res[2], res[3]); o.z = pk2(res[4], res[5]); o.w = pk2(res[6], res[7]);
;                     *(v4u*)(G + (size_t)gr * DFF + ch0) = o; }
.LBB0_1092:
	s_or_b64 exec, exec, s[52:53]
	s_addk_i32 s65, 0x7b
	v_add_u32_e32 v111, s65, v172
	v_cmp_gt_i32_e32 vcc, s86, v111
	v_mov_b32_dpp v115, v72 row_ror:15 row_mask:0xf bank_mask:0xf
	v_mov_b32_dpp v116, v73 row_ror:15 row_mask:0xf bank_mask:0xf
	v_mov_b32_dpp v117, v74 row_ror:15 row_mask:0xf bank_mask:0xf
	v_mov_b32_dpp v118, v75 row_ror:15 row_mask:0xf bank_mask:0xf
	v_mov_b32_dpp v119, v88 row_ror:15 row_mask:0xf bank_mask:0xf
	v_mov_b32_dpp v120, v89 row_ror:15 row_mask:0xf bank_mask:0xf
	v_mov_b32_dpp v113, v90 row_ror:15 row_mask:0xf bank_mask:0xf
	v_mov_b32_dpp v114, v91 row_ror:15 row_mask:0xf bank_mask:0xf
	v_mov_b32_dpp v101, v72 row_ror:1 row_mask:0xf bank_mask:0xf
	v_mov_b32_dpp v100, v44 row_ror:15 row_mask:0xf bank_mask:0xf
	v_mov_b32_dpp v98, v73 row_ror:1 row_mask:0xf bank_mask:0xf
	v_mov_b32_dpp v96, v45 row_ror:15 row_mask:0xf bank_mask:0xf
	v_mov_b32_dpp v105, v74 row_ror:1 row_mask:0xf bank_mask:0xf
	v_mov_b32_dpp v104, v46 row_ror:15 row_mask:0xf bank_mask:0xf
	v_mov_b32_dpp v103, v75 row_ror:1 row_mask:0xf bank_mask:0xf
	v_mov_b32_dpp v102, v47 row_ror:15 row_mask:0xf bank_mask:0xf
	v_mov_b32_dpp v109, v88 row_ror:1 row_mask:0xf bank_mask:0xf
	v_mov_b32_dpp v108, v40 row_ror:15 row_mask:0xf bank_mask:0xf
	v_mov_b32_dpp v107, v89 row_ror:1 row_mask:0xf bank_mask:0xf
	v_mov_b32_dpp v106, v41 row_ror:15 row_mask:0xf bank_mask:0xf
	v_mov_b32_dpp v112, v90 row_ror:1 row_mask:0xf bank_mask:0xf
	v_mov_b32_dpp v110, v42 row_ror:15 row_mask:0xf bank_mask:0xf
	v_mov_b32_dpp v99, v91 row_ror:1 row_mask:0xf bank_mask:0xf
	v_mov_b32_dpp v97, v43 row_ror:15 row_mask:0xf bank_mask:0xf
	s_and_b64 s[48:49], s[42:43], vcc
	s_and_saveexec_b64 s[52:53], s[48:49]
	s_cbranch_execz .LBB0_1094
	v_and_b32_e32 v121, 0x1fff, v111
	v_and_b32_e32 v122, 0xff, v111
	v_cmp_gt_i32_e32 vcc, s97, v111
	v_cmp_eq_u32_e64 s[48:49], s78, v121
	s_waitcnt vmcnt(0)
	v_pk_mul_f32 v[88:89], v[88:89], v[68:69]
	v_cndmask_b32_e32 v123, v122, v121, vcc
	v_cndmask_b32_e64 v121, 0, 1, s[48:49]
	v_cmp_eq_u32_e64 s[48:49], s12, v122
	v_cndmask_b32_e64 v119, v119, v108, s[40:41]
	v_cndmask_b32_e64 v120, v120, v106, s[40:41]
	v_cndmask_b32_e64 v122, 0, 1, s[48:49]
	v_cndmask_b32_e32 v121, v122, v121, vcc
	v_and_b32_e32 v121, 1, v121
	v_cmp_eq_u32_e32 vcc, 0, v123
	v_cmp_eq_u32_e64 s[48:49], 1, v121
	v_pk_mul_f32 v[72:73], v[72:73], v[92:93]
	v_cndmask_b32_e64 v123, v107, 0, vcc
	v_cndmask_b32_e64 v122, v109, 0, vcc
	v_pk_fma_f32 v[88:89], v[56:57], v[122:123], v[88:89]
	v_cndmask_b32_e64 v121, v120, 0, s[48:49]
	v_cndmask_b32_e64 v120, v119, 0, s[48:49]
	v_pk_fma_f32 v[88:89], v[60:61], v[120:121], v[88:89]
	v_cndmask_b32_e64 v115, v115, v100, s[40:41]
	v_pk_add_f32 v[88:89], v[64:65], v[88:89]
	v_cndmask_b32_e64 v116, v116, v96, s[40:41]
	v_mul_f32_e32 v119, 0x3d372713, v88
	v_mul_f32_e32 v119, v88, v119
	v_mul_f32_e32 v120, 0x3d372713, v89
	v_fma_f32 v119, v88, v119, v88
	v_mul_f32_e32 v120, v89, v120
	v_mul_f32_e32 v119, 0xc0135761, v119
	v_fma_f32 v120, v89, v120, v89
	v_exp_f32_e32 v119, v119
	v_mul_f32_e32 v120, 0xc0135761, v120
	v_exp_f32_e32 v121, v120
	v_pk_mul_f32 v[90:91], v[90:91], v[70:71]
	v_add_f32_e32 v119, 1.0, v119
	v_rcp_f32_e32 v120, v119
	v_add_f32_e32 v119, 1.0, v121
	v_rcp_f32_e32 v121, v119
	v_cndmask_b32_e64 v119, v98, 0, vcc
	v_cndmask_b32_e64 v113, v113, v110, s[40:41]
	v_cndmask_b32_e64 v114, v114, v97, s[40:41]
	v_pk_mul_f32 v[88:89], v[88:89], v[120:121]
	s_nop 0
	v_pk_mul_f32 v[88:89], v[48:49], v[88:89]
	v_pk_mul_f32 v[48:49], v[74:75], v[94:95]
	v_cndmask_b32_e64 v75, v103, 0, vcc
	v_cndmask_b32_e64 v74, v105, 0, vcc
	v_pk_fma_f32 v[48:49], v[78:79], v[74:75], v[48:49]
	v_cndmask_b32_e64 v74, v117, v104, s[40:41]
	v_cndmask_b32_e64 v75, v118, v102, s[40:41]
	v_cndmask_b32_e64 v75, v75, 0, s[48:49]
	v_cndmask_b32_e64 v74, v74, 0, s[48:49]
	v_pk_fma_f32 v[48:49], v[82:83], v[74:75], v[48:49]
	v_cndmask_b32_e64 v118, v101, 0, vcc
	v_pk_add_f32 v[48:49], v[86:87], v[48:49]
	v_pk_fma_f32 v[72:73], v[76:77], v[118:119], v[72:73]
	v_mul_f32_e32 v74, 0x3d372713, v48
	v_mul_f32_e32 v75, 0x3d372713, v49
	v_mul_f32_e32 v74, v48, v74
	v_mul_f32_e32 v75, v49, v75
	v_fma_f32 v74, v48, v74, v48
	v_fma_f32 v75, v49, v75, v49
	v_cndmask_b32_e64 v117, v116, 0, s[48:49]
	v_cndmask_b32_e64 v116, v115, 0, s[48:49]
	v_mul_f32_e32 v74, 0xc0135761, v74
	v_mul_f32_e32 v75, 0xc0135761, v75
	v_pk_fma_f32 v[72:73], v[80:81], v[116:117], v[72:73]
	v_exp_f32_e32 v74, v74
	v_exp_f32_e32 v75, v75
	v_pk_add_f32 v[72:73], v[84:85], v[72:73]
	v_cndmask_b32_e64 v117, v99, 0, vcc
	v_mul_f32_e32 v116, 0x3d372713, v73
	v_mul_f32_e32 v115, 0x3d372713, v72
	v_mul_f32_e32 v116, v73, v116
	v_mul_f32_e32 v115, v72, v115
	v_fma_f32 v116, v73, v116, v73
	v_add_f32_e32 v74, 1.0, v74
	v_add_f32_e32 v75, 1.0, v75
	v_fma_f32 v115, v72, v115, v72
	v_mul_f32_e32 v116, 0xc0135761, v116
	v_rcp_f32_e32 v74, v74
	v_rcp_f32_e32 v75, v75
	v_mul_f32_e32 v115, 0xc0135761, v115
	v_exp_f32_e32 v116, v116
	v_exp_f32_e32 v115, v115
	v_pk_mul_f32 v[48:49], v[48:49], v[74:75]
	v_add_f32_e32 v75, 1.0, v116
	v_cndmask_b32_e64 v116, v112, 0, vcc
	v_add_f32_e32 v74, 1.0, v115
	v_pk_fma_f32 v[90:91], v[58:59], v[116:117], v[90:91]
	v_cndmask_b32_e64 v115, v114, 0, s[48:49]
	v_cndmask_b32_e64 v114, v113, 0, s[48:49]
	v_pk_fma_f32 v[90:91], v[62:63], v[114:115], v[90:91]
	v_rcp_f32_e32 v74, v74
	v_pk_add_f32 v[90:91], v[66:67], v[90:91]
	v_rcp_f32_e32 v75, v75
	v_mul_f32_e32 v113, 0x3d372713, v90
	v_mul_f32_e32 v113, v90, v113
	v_mul_f32_e32 v114, 0x3d372713, v91
	v_fma_f32 v113, v90, v113, v90
	v_mul_f32_e32 v114, v91, v114
	v_mul_f32_e32 v113, 0xc0135761, v113
	v_fma_f32 v114, v91, v114, v91
	v_exp_f32_e32 v113, v113
	v_mul_f32_e32 v114, 0xc0135761, v114
	v_exp_f32_e32 v115, v114
	v_pk_mul_f32 v[54:55], v[54:55], v[48:49]
	v_add_f32_e32 v113, 1.0, v113
	v_rcp_f32_e32 v114, v113
	v_add_f32_e32 v113, 1.0, v115
	v_rcp_f32_e32 v115, v113
	v_pk_mul_f32 v[48:49], v[72:73], v[74:75]
	s_nop 0
	v_pk_mul_f32 v[48:49], v[52:53], v[48:49]
	v_pk_mul_f32 v[52:53], v[90:91], v[114:115]
	v_cvt_pk_bf16_f32 v48, v48, v49
	v_pk_mul_f32 v[52:53], v[50:51], v[52:53]
	v_cvt_pk_bf16_f32 v49, v54, v55
	v_cvt_pk_bf16_f32 v51, v52, v53
	v_mov_b64_e32 v[52:53], s[6:7]
	v_mad_i64_i32 v[52:53], s[48:49], v111, s1, v[52:53]
	v_cvt_pk_bf16_f32 v50, v88, v89
	v_lshl_add_u64 v[52:53], v[170:171], 1, v[52:53]
	global_store_dwordx4 v[52:53], v[48:51], off
; __device__ __forceinline__ float dpp_ror1(float v) { return __builtin_bit_cast(float, __builtin_amdgcn_update_dpp(0, __builtin_bit_cast(int, v), 0x121, 0xF, 0xF, false)); }
; __device__ __forceinline__ float dpp_rol1(float v) { return __builtin_bit_cast(float, __builtin_amdgcn_update_dpp(0, __builtin_bit_cast(int, v), 0x12F, 0xF, 0xF, false)); }
;     __device__ __forceinline__ void operator()(const pg8::f32x4 (&acc)[2][2][4][2], const pg8::Unit& u, int wr, int wc, int fr, int fq) const {
;     ...
;                 bool first, last; if (gr < ML) { const int t = gr & 8191; first = t == 0; last = t == 8191; } else { const int t = (gr - ML) & 255; first = t == 0; last = t == 255; }
;                 float res[8];
; #pragma unroll
;                 for (int c = 0; c < 8; ++c) {
;                     const int n = c >> 2, e = c & 3;
;                     const float x0 = acc[ai][0][m][n][e];
;                     const float ruC = dpp_ror1(x0), rdN = m < 3 ? dpp_rol1(acc[ai][0][m < 3 ? m + 1 : 3][n][e]) : 0.f;
;                     float xu = fr == 0 ? ruP[c] : ruC, xd = fr == 15 ? rdN : rdC[c];
;                     xu = first ? 0.f : xu; xd = last ? 0.f : xd;
;                     ruP[c] = ruC; rdC[c] = rdN;
;                     const float x = w0[c] * xu + w1[c] * x0 + w2[c] * xd + bb[c];
;                     const float u2 = -2.302208198f * (x + 0.044715f * x * x * x);
;                     res[c] = x * __builtin_amdgcn_rcpf(1.0f + __builtin_amdgcn_exp2f(u2)) * acc[ai][1][m][n][e];
.LBB0_1094:
	s_or_b64 exec, exec, s[52:53]
	v_add_u32_e32 v111, s65, v174
	v_mov_b32_dpp v53, v44 row_ror:1 row_mask:0xf bank_mask:0xf
	v_mov_b32_dpp v52, v28 row_ror:15 row_mask:0xf bank_mask:0xf
	v_mov_b32_dpp v50, v45 row_ror:1 row_mask:0xf bank_mask:0xf
	v_mov_b32_dpp v48, v29 row_ror:15 row_mask:0xf bank_mask:0xf
	v_mov_b32_dpp v73, v46 row_ror:1 row_mask:0xf bank_mask:0xf
	v_mov_b32_dpp v72, v30 row_ror:15 row_mask:0xf bank_mask:0xf
	v_mov_b32_dpp v55, v47 row_ror:1 row_mask:0xf bank_mask:0xf
	v_mov_b32_dpp v54, v31 row_ror:15 row_mask:0xf bank_mask:0xf
	v_mov_b32_dpp v89, v40 row_ror:1 row_mask:0xf bank_mask:0xf
	v_mov_b32_dpp v88, v24 row_ror:15 row_mask:0xf bank_mask:0xf
	v_mov_b32_dpp v75, v41 row_ror:1 row_mask:0xf bank_mask:0xf
	v_mov_b32_dpp v74, v25 row_ror:15 row_mask:0xf bank_mask:0xf
	v_mov_b32_dpp v91, v42 row_ror:1 row_mask:0xf bank_mask:0xf
	v_mov_b32_dpp v90, v26 row_ror:15 row_mask:0xf bank_mask:0xf
	v_mov_b32_dpp v51, v43 row_ror:1 row_mask:0xf bank_mask:0xf
	v_mov_b32_dpp v49, v27 row_ror:15 row_mask:0xf bank_mask:0xf
	v_cmp_gt_i32_e32 vcc, s86, v111
	s_and_saveexec_b64 s[80:81], vcc
	s_cbranch_execz .LBB0_1096
	v_and_b32_e32 v116, 0x1fff, v111
	v_and_b32_e32 v117, 0xff, v111
	v_cmp_gt_i32_e64 s[48:49], s97, v111
	v_cndmask_b32_e64 v112, v91, v112, s[38:39]
	v_mov_b32_e32 v114, v42
	v_cndmask_b32_e64 v113, v117, v116, s[48:49]
	v_cmp_eq_u32_e32 vcc, 0, v113
	s_waitcnt vmcnt(0)
	v_mov_b32_e32 v115, v58
	v_cmp_eq_u32_e64 s[52:53], s78, v116
	v_cndmask_b32_e64 v113, v112, 0, vcc
	v_mov_b32_e32 v112, v70
	v_pk_mul_f32 v[112:113], v[114:115], v[112:113]
	v_cndmask_b32_e64 v109, v89, v109, s[38:39]
	v_add_f32_e32 v42, v112, v113
	v_cndmask_b32_e64 v112, 0, 1, s[52:53]
	v_cmp_eq_u32_e64 s[52:53], s12, v117
	v_cndmask_b32_e64 v110, v110, v90, s[40:41]
	v_mov_b32_e32 v114, v40
	v_cndmask_b32_e64 v113, 0, 1, s[52:53]
	v_cndmask_b32_e64 v112, v113, v112, s[48:49]
	v_and_b32_e32 v112, 1, v112
	v_cmp_eq_u32_e64 s[48:49], 1, v112
	v_cndmask_b32_e64 v113, v109, 0, vcc
	v_mov_b32_e32 v115, v56
	v_mov_b32_e32 v112, v68
	v_cndmask_b32_e64 v110, v110, 0, s[48:49]
	v_pk_mul_f32 v[112:113], v[114:115], v[112:113]
	v_cndmask_b32_e64 v108, v108, v88, s[40:41]
	v_fmac_f32_e32 v42, v62, v110
	v_add_f32_e32 v40, v112, v113
	v_cndmask_b32_e64 v108, v108, 0, s[48:49]
	v_add_f32_e32 v42, v66, v42
	v_fmac_f32_e32 v40, v60, v108
	v_mul_f32_e32 v110, 0x3d372713, v42
	v_add_f32_e32 v40, v64, v40
	v_mul_f32_e32 v110, v42, v110
	v_mul_f32_e32 v108, 0x3d372713, v40
	v_fma_f32 v110, v42, v110, v42
	v_mul_f32_e32 v108, v40, v108
	v_mul_f32_e32 v110, 0xc0135761, v110
	v_fma_f32 v108, v40, v108, v40
	v_exp_f32_e32 v110, v110
	v_mul_f32_e32 v108, 0xc0135761, v108
	v_exp_f32_e32 v108, v108
	v_add_f32_e32 v109, 1.0, v110
	v_rcp_f32_e32 v109, v109
	v_add_f32_e32 v108, 1.0, v108
	v_rcp_f32_e32 v108, v108
	v_mul_f32_e32 v42, v42, v109
	v_mul_f32_e32 v42, v34, v42
	v_mul_f32_e32 v34, v40, v108
	v_cndmask_b32_e64 v40, v75, v107, s[38:39]
	v_cndmask_b32_e64 v109, v40, 0, vcc
	v_mov_b32_e32 v40, v41
	v_mov_b32_e32 v41, v57
	v_mov_b32_e32 v108, v69
	v_pk_mul_f32 v[40:41], v[40:41], v[108:109]
	v_mov_b32_e32 v107, v78
	v_add_f32_e32 v40, v40, v41
	v_cndmask_b32_e64 v41, v106, v74, s[40:41]
	v_cndmask_b32_e64 v41, v41, 0, s[48:49]
	v_fmac_f32_e32 v40, v61, v41
	v_add_f32_e32 v108, v65, v40
	v_mul_f32_e32 v40, 0x3d372713, v108
	v_mul_f32_e32 v40, v108, v40
	v_fma_f32 v40, v108, v40, v108
	v_mul_f32_e32 v40, 0xc0135761, v40
	v_exp_f32_e32 v109, v40
	v_cndmask_b32_e64 v40, v73, v105, s[38:39]
	v_cndmask_b32_e64 v41, v40, 0, vcc
	v_mov_b32_e32 v106, v46
	v_mov_b32_e32 v40, v94
	v_pk_mul_f32 v[40:41], v[106:107], v[40:41]
	v_mov_b32_e32 v46, v47
	v_add_f32_e32 v40, v40, v41
	v_cndmask_b32_e64 v41, v104, v72, s[40:41]
	v_cndmask_b32_e64 v41, v41, 0, s[48:49]
	v_fmac_f32_e32 v40, v82, v41
	v_add_f32_e32 v104, v86, v40
	v_mul_f32_e32 v40, 0x3d372713, v104
	v_mul_f32_e32 v40, v104, v40
	v_fma_f32 v40, v104, v40, v104
	v_mul_f32_e32 v40, 0xc0135761, v40
	v_exp_f32_e32 v40, v40
	v_mov_b32_e32 v47, v79
	v_mul_f32_e32 v34, v32, v34
	v_add_f32_e32 v32, 1.0, v109
	v_add_f32_e32 v40, 1.0, v40
	v_rcp_f32_e32 v105, v40
	v_cndmask_b32_e64 v40, v55, v103, s[38:39]
	v_cndmask_b32_e64 v41, v40, 0, vcc
	v_mov_b32_e32 v40, v95
	v_pk_mul_f32 v[40:41], v[46:47], v[40:41]
	v_rcp_f32_e32 v32, v32
	v_add_f32_e32 v40, v40, v41
	v_cndmask_b32_e64 v41, v102, v54, s[40:41]
	v_cndmask_b32_e64 v41, v41, 0, s[48:49]
	v_fmac_f32_e32 v40, v83, v41
	v_add_f32_e32 v46, v87, v40
	v_mul_f32_e32 v40, 0x3d372713, v46
	v_mul_f32_e32 v40, v46, v40
	v_fma_f32 v40, v46, v40, v46
	v_mul_f32_e32 v40, 0xc0135761, v40
	v_exp_f32_e32 v40, v40
	v_mul_f32_e32 v32, v108, v32
	v_mul_f32_e32 v47, v33, v32
	v_mov_b32_e32 v41, v76
	v_add_f32_e32 v32, 1.0, v40
	v_rcp_f32_e32 v103, v32
	v_cndmask_b32_e64 v32, v53, v101, s[38:39]
	v_cndmask_b32_e64 v33, v32, 0, vcc
	v_mov_b32_e32 v40, v44
	v_mov_b32_e32 v32, v92
	v_pk_mul_f32 v[32:33], v[40:41], v[32:33]
	v_mul_f32_e32 v102, v104, v105
	v_add_f32_e32 v32, v32, v33
	v_cndmask_b32_e64 v33, v100, v52, s[40:41]
	v_cndmask_b32_e64 v33, v33, 0, s[48:49]
	v_fmac_f32_e32 v32, v80, v33
	v_add_f32_e32 v40, v84, v32
	v_mul_f32_e32 v32, 0x3d372713, v40
	v_mul_f32_e32 v32, v40, v32
	v_fma_f32 v32, v40, v32, v40
	v_mul_f32_e32 v32, 0xc0135761, v32
	v_exp_f32_e32 v32, v32
	v_mul_f32_e32 v33, v46, v103
	v_mul_f32_e32 v41, v38, v102
	v_mul_f32_e32 v44, v39, v33
	v_add_f32_e32 v32, 1.0, v32
	v_rcp_f32_e32 v46, v32
	v_cndmask_b32_e64 v32, v50, v98, s[38:39]
	v_cndmask_b32_e64 v33, v32, 0, vcc
	v_mov_b32_e32 v38, v45
	v_mov_b32_e32 v39, v77
	v_mov_b32_e32 v32, v93
	v_pk_mul_f32 v[32:33], v[38:39], v[32:33]
; __device__ __forceinline__ unsigned pk2(float lo, float hi) { const f32x2_cv v = {lo, hi}; const bf16x2_cv b = __builtin_convertvector(v, bf16x2_cv); return __builtin_bit_cast(unsigned, b); }
; __device__ __forceinline__ float dpp_ror1(float v) { return __builtin_bit_cast(float, __builtin_amdgcn_update_dpp(0, __builtin_bit_cast(int, v), 0x121, 0xF, 0xF, false)); }
; __device__ __forceinline__ float dpp_rol1(float v) { return __builtin_bit_cast(float, __builtin_amdgcn_update_dpp(0, __builtin_bit_cast(int, v), 0x12F, 0xF, 0xF, false)); }
;     __device__ __forceinline__ void operator()(const pg8::f32x4 (&acc)[2][2][4][2], const pg8::Unit& u, int wr, int wc, int fr, int fq) const {
;     ...
;                 const int rl = 16 * m + fr, gr = 62 * kb - 1 + rl;
;                 bool first, last; if (gr < ML) { const int t = gr & 8191; first = t == 0; last = t == 8191; } else { const int t = (gr - ML) & 255; first = t == 0; last = t == 255; }
;                 float res[8];
; #pragma unroll
;                 for (int c = 0; c < 8; ++c) {
;                     const int n = c >> 2, e = c & 3;
;                     const float x0 = acc[ai][0][m][n][e];
;                     const float ruC = dpp_ror1(x0), rdN = m < 3 ? dpp_rol1(acc[ai][0][m < 3 ? m + 1 : 3][n][e]) : 0.f;
;                     float xu = fr == 0 ? ruP[c] : ruC, xd = fr == 15 ? rdN : rdC[c];
;                     xu = first ? 0.f : xu; xd = last ? 0.f : xd;
;                     ruP[c] = ruC; rdC[c] = rdN;
;                     const float x = w0[c] * xu + w1[c] * x0 + w2[c] * xd + bb[c];
;                     const float u2 = -2.302208198f * (x + 0.044715f * x * x * x);
;                     res[c] = x * __builtin_amdgcn_rcpf(1.0f + __builtin_amdgcn_exp2f(u2)) * acc[ai][1][m][n][e];
;                 }
;                 if (rl >= 1 && rl <= 62 && gr < nrows) { v4u o; o.x = pk2(res[0], res[1]); o.y = pk2(res[2], res[3]); o.z = pk2(res[4], res[5]); o.w = pk2(res[6], res[7]);
;                     *(v4u*)(G + (size_t)gr * DFF + ch0) = o; }
	v_mov_b32_e32 v38, v43
	v_add_f32_e32 v32, v32, v33
	v_cndmask_b32_e64 v33, v96, v48, s[40:41]
	v_cndmask_b32_e64 v33, v33, 0, s[48:49]
	v_fmac_f32_e32 v32, v81, v33
	v_add_f32_e32 v45, v85, v32
	v_mul_f32_e32 v32, 0x3d372713, v45
	v_mul_f32_e32 v32, v45, v32
	v_fma_f32 v32, v45, v32, v45
	v_mul_f32_e32 v32, 0xc0135761, v32
	v_exp_f32_e32 v96, v32
	v_cndmask_b32_e64 v32, v51, v99, s[38:39]
	v_cndmask_b32_e64 v33, v32, 0, vcc
	v_mov_b32_e32 v39, v59
	v_mov_b32_e32 v32, v71
	v_pk_mul_f32 v[32:33], v[38:39], v[32:33]
	v_add_f32_e32 v39, 1.0, v96
	v_add_f32_e32 v32, v32, v33
	v_cndmask_b32_e64 v33, v97, v49, s[40:41]
	v_cndmask_b32_e64 v33, v33, 0, s[48:49]
	v_fmac_f32_e32 v32, v63, v33
	v_add_f32_e32 v32, v67, v32
	v_mul_f32_e32 v33, 0x3d372713, v32
	v_mul_f32_e32 v33, v32, v33
	v_fma_f32 v33, v32, v33, v32
	v_mul_f32_e32 v33, 0xc0135761, v33
	v_exp_f32_e32 v33, v33
	v_rcp_f32_e32 v39, v39
	v_mul_f32_e32 v38, v40, v46
	v_mul_f32_e32 v36, v36, v38
	v_add_f32_e32 v33, 1.0, v33
	v_rcp_f32_e32 v33, v33
	v_mul_f32_e32 v38, v45, v39
	v_mul_f32_e32 v37, v37, v38
	v_cvt_pk_bf16_f32 v34, v34, v47
	v_mul_f32_e32 v32, v32, v33
	v_mul_f32_e32 v35, v35, v32
	v_cvt_pk_bf16_f32 v32, v36, v37
	v_mov_b64_e32 v[36:37], s[6:7]
	v_mad_i64_i32 v[36:37], s[48:49], v111, s1, v[36:37]
	v_cvt_pk_bf16_f32 v33, v41, v44
	v_cvt_pk_bf16_f32 v35, v42, v35
	v_lshl_add_u64 v[36:37], v[170:171], 1, v[36:37]
	global_store_dwordx4 v[36:37], v[32:35], off
.LBB0_1096:
	s_or_b64 exec, exec, s[80:81]
	v_add_u32_e32 v96, s65, v175
	v_mov_b32_dpp v46, v28 row_ror:1 row_mask:0xf bank_mask:0xf
	v_mov_b32_dpp v44, v12 row_ror:15 row_mask:0xf bank_mask:0xf
	v_mov_b32_dpp v47, v29 row_ror:1 row_mask:0xf bank_mask:0xf
	v_mov_b32_dpp v45, v13 row_ror:15 row_mask:0xf bank_mask:0xf
	v_mov_b32_dpp v42, v30 row_ror:1 row_mask:0xf bank_mask:0xf
	v_mov_b32_dpp v40, v14 row_ror:15 row_mask:0xf bank_mask:0xf
	v_mov_b32_dpp v43, v31 row_ror:1 row_mask:0xf bank_mask:0xf
	v_mov_b32_dpp v41, v15 row_ror:15 row_mask:0xf bank_mask:0xf
	v_mov_b32_dpp v38, v24 row_ror:1 row_mask:0xf bank_mask:0xf
	v_mov_b32_dpp v36, v8 row_ror:15 row_mask:0xf bank_mask:0xf
	v_mov_b32_dpp v39, v25 row_ror:1 row_mask:0xf bank_mask:0xf
	v_mov_b32_dpp v37, v9 row_ror:15 row_mask:0xf bank_mask:0xf
	v_mov_b32_dpp v34, v26 row_ror:1 row_mask:0xf bank_mask:0xf
	v_mov_b32_dpp v32, v10 row_ror:15 row_mask:0xf bank_mask:0xf
	v_mov_b32_dpp v35, v27 row_ror:1 row_mask:0xf bank_mask:0xf
	v_mov_b32_dpp v33, v11 row_ror:15 row_mask:0xf bank_mask:0xf
	v_cmp_gt_i32_e32 vcc, s86, v96
	s_and_saveexec_b64 s[80:81], vcc
	s_cbranch_execz .LBB0_1098
	v_and_b32_e32 v97, 0x1fff, v96
	v_and_b32_e32 v102, 0xff, v96
	v_cmp_gt_i32_e64 s[48:49], s97, v96
	v_cndmask_b32_e64 v91, v34, v91, s[38:39]
	v_cmp_eq_u32_e64 s[52:53], s78, v97
	v_cndmask_b32_e64 v98, v102, v97, s[48:49]
	v_cmp_eq_u32_e32 vcc, 0, v98
	v_mov_b32_e32 v100, v26
	s_waitcnt vmcnt(0)
	v_mov_b32_e32 v101, v58
	v_cndmask_b32_e64 v99, v91, 0, vcc
	v_cndmask_b32_e64 v91, 0, 1, s[52:53]
	v_cmp_eq_u32_e64 s[52:53], s12, v102
	v_mov_b32_e32 v98, v70
	v_pk_mul_f32 v[98:99], v[100:101], v[98:99]
	v_cndmask_b32_e64 v97, 0, 1, s[52:53]
	v_cndmask_b32_e64 v91, v97, v91, s[48:49]
	v_and_b32_e32 v91, 1, v91
	v_cndmask_b32_e64 v90, v90, v32, s[40:41]
	v_cmp_eq_u32_e64 s[48:49], 1, v91
	v_add_f32_e32 v26, v98, v99
	v_cndmask_b32_e64 v89, v38, v89, s[38:39]
	v_cndmask_b32_e64 v90, v90, 0, s[48:49]
	v_fmac_f32_e32 v26, v62, v90
	v_add_f32_e32 v26, v66, v26
	v_mul_f32_e32 v90, 0x3d372713, v26
	v_mul_f32_e32 v90, v26, v90
	v_fma_f32 v90, v26, v90, v26
	v_mul_f32_e32 v90, 0xc0135761, v90
	v_exp_f32_e32 v97, v90
	v_cndmask_b32_e64 v91, v89, 0, vcc
	v_mov_b32_e32 v98, v24
	v_mov_b32_e32 v99, v56
	v_mov_b32_e32 v90, v68
	v_pk_mul_f32 v[90:91], v[98:99], v[90:91]
	v_cndmask_b32_e64 v88, v88, v36, s[40:41]
	v_add_f32_e32 v24, v90, v91
	v_cndmask_b32_e64 v88, v88, 0, s[48:49]
	v_fmac_f32_e32 v24, v60, v88
	v_add_f32_e32 v24, v64, v24
	v_mul_f32_e32 v88, 0x3d372713, v24
	v_mul_f32_e32 v88, v24, v88
	v_fma_f32 v88, v24, v88, v24
	v_mul_f32_e32 v88, 0xc0135761, v88
	v_exp_f32_e32 v88, v88
	v_add_f32_e32 v89, 1.0, v97
	v_rcp_f32_e32 v89, v89
	v_add_f32_e32 v88, 1.0, v88
	v_rcp_f32_e32 v88, v88
	v_mul_f32_e32 v26, v26, v89
	v_mul_f32_e32 v26, v18, v26
	v_mul_f32_e32 v18, v24, v88
	v_cndmask_b32_e64 v24, v39, v75, s[38:39]
	v_cndmask_b32_e64 v89, v24, 0, vcc
	v_mov_b32_e32 v24, v25
	v_mov_b32_e32 v25, v57
	v_mov_b32_e32 v88, v69
	v_pk_mul_f32 v[24:25], v[24:25], v[88:89]
	v_mov_b32_e32 v75, v78
	v_add_f32_e32 v24, v24, v25
	v_cndmask_b32_e64 v25, v74, v37, s[40:41]
	v_cndmask_b32_e64 v25, v25, 0, s[48:49]
	v_fmac_f32_e32 v24, v61, v25
	v_add_f32_e32 v88, v65, v24
	v_mul_f32_e32 v24, 0x3d372713, v88
	v_mul_f32_e32 v24, v88, v24
	v_fma_f32 v24, v88, v24, v88
	v_mul_f32_e32 v24, 0xc0135761, v24
	v_exp_f32_e32 v89, v24
	v_cndmask_b32_e64 v24, v42, v73, s[38:39]
	v_cndmask_b32_e64 v25, v24, 0, vcc
	v_mov_b32_e32 v74, v30
	v_mov_b32_e32 v24, v94
	v_pk_mul_f32 v[24:25], v[74:75], v[24:25]
	v_mov_b32_e32 v30, v31
	v_add_f32_e32 v24, v24, v25
	v_cndmask_b32_e64 v25, v72, v40, s[40:41]
	v_cndmask_b32_e64 v25, v25, 0, s[48:49]
	v_fmac_f32_e32 v24, v82, v25
	v_add_f32_e32 v72, v86, v24
	v_mul_f32_e32 v24, 0x3d372713, v72
	v_mul_f32_e32 v24, v72, v24
	v_fma_f32 v24, v72, v24, v72
	v_mul_f32_e32 v24, 0xc0135761, v24
	v_exp_f32_e32 v24, v24
	v_mov_b32_e32 v31, v79
	v_mul_f32_e32 v18, v16, v18
	v_add_f32_e32 v16, 1.0, v89
	v_add_f32_e32 v24, 1.0, v24
	v_rcp_f32_e32 v73, v24
	v_cndmask_b32_e64 v24, v43, v55, s[38:39]
	v_cndmask_b32_e64 v25, v24, 0, vcc
	v_mov_b32_e32 v24, v95
	v_pk_mul_f32 v[24:25], v[30:31], v[24:25]
; __device__ __forceinline__ unsigned pk2(float lo, float hi) { const f32x2_cv v = {lo, hi}; const bf16x2_cv b = __builtin_convertvector(v, bf16x2_cv); return __builtin_bit_cast(unsigned, b); }
; __device__ __forceinline__ float dpp_ror1(float v) { return __builtin_bit_cast(float, __builtin_amdgcn_update_dpp(0, __builtin_bit_cast(int, v), 0x121, 0xF, 0xF, false)); }
; __device__ __forceinline__ float dpp_rol1(float v) { return __builtin_bit_cast(float, __builtin_amdgcn_update_dpp(0, __builtin_bit_cast(int, v), 0x12F, 0xF, 0xF, false)); }
;     __device__ __forceinline__ void operator()(const pg8::f32x4 (&acc)[2][2][4][2], const pg8::Unit& u, int wr, int wc, int fr, int fq) const {
;     ...
;                 for (int c = 0; c < 8; ++c) {
;                     const int n = c >> 2, e = c & 3;
;                     const float x0 = acc[ai][0][m][n][e];
;                     const float ruC = dpp_ror1(x0), rdN = m < 3 ? dpp_rol1(acc[ai][0][m < 3 ? m + 1 : 3][n][e]) : 0.f;
;                     float xu = fr == 0 ? ruP[c] : ruC, xd = fr == 15 ? rdN : rdC[c];
;                     xu = first ? 0.f : xu; xd = last ? 0.f : xd;
;                     ruP[c] = ruC; rdC[c] = rdN;
;                     const float x = w0[c] * xu + w1[c] * x0 + w2[c] * xd + bb[c];
;                     const float u2 = -2.302208198f * (x + 0.044715f * x * x * x);
;                     res[c] = x * __builtin_amdgcn_rcpf(1.0f + __builtin_amdgcn_exp2f(u2)) * acc[ai][1][m][n][e];
;                 }
;                 if (rl >= 1 && rl <= 62 && gr < nrows) { v4u o; o.x = pk2(res[0], res[1]); o.y = pk2(res[2], res[3]); o.z = pk2(res[4], res[5]); o.w = pk2(res[6], res[7]);
;                     *(v4u*)(G + (size_t)gr * DFF + ch0) = o; }
	v_rcp_f32_e32 v16, v16
	v_add_f32_e32 v24, v24, v25
	v_cndmask_b32_e64 v25, v54, v41, s[40:41]
	v_cndmask_b32_e64 v25, v25, 0, s[48:49]
	v_fmac_f32_e32 v24, v83, v25
	v_add_f32_e32 v30, v87, v24
	v_mul_f32_e32 v24, 0x3d372713, v30
	v_mul_f32_e32 v24, v30, v24
	v_fma_f32 v24, v30, v24, v30
	v_mul_f32_e32 v24, 0xc0135761, v24
	v_exp_f32_e32 v24, v24
	v_mul_f32_e32 v16, v88, v16
	v_mul_f32_e32 v31, v17, v16
	v_mov_b32_e32 v25, v76
	v_add_f32_e32 v16, 1.0, v24
	v_rcp_f32_e32 v55, v16
	v_cndmask_b32_e64 v16, v46, v53, s[38:39]
	v_cndmask_b32_e64 v17, v16, 0, vcc
	v_mov_b32_e32 v24, v28
	v_mov_b32_e32 v16, v92
	v_pk_mul_f32 v[16:17], v[24:25], v[16:17]
	v_mul_f32_e32 v54, v72, v73
	v_add_f32_e32 v16, v16, v17
	v_cndmask_b32_e64 v17, v52, v44, s[40:41]
	v_cndmask_b32_e64 v17, v17, 0, s[48:49]
	v_fmac_f32_e32 v16, v80, v17
	v_add_f32_e32 v24, v84, v16
	v_mul_f32_e32 v16, 0x3d372713, v24
	v_mul_f32_e32 v16, v24, v16
	v_fma_f32 v16, v24, v16, v24
	v_mul_f32_e32 v16, 0xc0135761, v16
	v_exp_f32_e32 v16, v16
	v_mul_f32_e32 v17, v30, v55
	v_mul_f32_e32 v25, v22, v54
	v_mul_f32_e32 v28, v23, v17
	v_add_f32_e32 v16, 1.0, v16
	v_rcp_f32_e32 v30, v16
	v_cndmask_b32_e64 v16, v47, v50, s[38:39]
	v_cndmask_b32_e64 v17, v16, 0, vcc
	v_mov_b32_e32 v22, v29
	v_mov_b32_e32 v23, v77
	v_mov_b32_e32 v16, v93
	v_pk_mul_f32 v[16:17], v[22:23], v[16:17]
	v_mov_b32_e32 v22, v27
	v_add_f32_e32 v16, v16, v17
	v_cndmask_b32_e64 v17, v48, v45, s[40:41]
	v_cndmask_b32_e64 v17, v17, 0, s[48:49]
	v_fmac_f32_e32 v16, v81, v17
	v_add_f32_e32 v29, v85, v16
	v_mul_f32_e32 v16, 0x3d372713, v29
	v_mul_f32_e32 v16, v29, v16
	v_fma_f32 v16, v29, v16, v29
	v_mul_f32_e32 v16, 0xc0135761, v16
	v_exp_f32_e32 v48, v16
	v_cndmask_b32_e64 v16, v35, v51, s[38:39]
	v_cndmask_b32_e64 v17, v16, 0, vcc
	v_mov_b32_e32 v23, v59
	v_mov_b32_e32 v16, v71
	v_pk_mul_f32 v[16:17], v[22:23], v[16:17]
	v_add_f32_e32 v23, 1.0, v48
	v_add_f32_e32 v16, v16, v17
	v_cndmask_b32_e64 v17, v49, v33, s[40:41]
	v_cndmask_b32_e64 v17, v17, 0, s[48:49]
	v_fmac_f32_e32 v16, v63, v17
	v_add_f32_e32 v16, v67, v16
	v_mul_f32_e32 v17, 0x3d372713, v16
	v_mul_f32_e32 v17, v16, v17
	v_fma_f32 v17, v16, v17, v16
	v_mul_f32_e32 v17, 0xc0135761, v17
	v_exp_f32_e32 v17, v17
	v_rcp_f32_e32 v23, v23
	v_mul_f32_e32 v22, v24, v30
	v_mul_f32_e32 v20, v20, v22
	v_add_f32_e32 v17, 1.0, v17
	v_rcp_f32_e32 v17, v17
	v_mul_f32_e32 v22, v29, v23
	v_mul_f32_e32 v21, v21, v22
	v_cvt_pk_bf16_f32 v18, v18, v31
	v_mul_f32_e32 v16, v16, v17
	v_mul_f32_e32 v19, v19, v16
	v_cvt_pk_bf16_f32 v16, v20, v21
	v_mov_b64_e32 v[20:21], s[6:7]
	v_mad_i64_i32 v[20:21], s[48:49], v96, s1, v[20:21]
	v_cvt_pk_bf16_f32 v17, v25, v28
	v_cvt_pk_bf16_f32 v19, v26, v19
	v_lshl_add_u64 v[20:21], v[170:171], 1, v[20:21]
	global_store_dwordx4 v[20:21], v[16:19], off
; __device__ __forceinline__ unsigned pk2(float lo, float hi) { const f32x2_cv v = {lo, hi}; const bf16x2_cv b = __builtin_convertvector(v, bf16x2_cv); return __builtin_bit_cast(unsigned, b); }
; __device__ __forceinline__ float dpp_ror1(float v) { return __builtin_bit_cast(float, __builtin_amdgcn_update_dpp(0, __builtin_bit_cast(int, v), 0x121, 0xF, 0xF, false)); }
; __device__ __forceinline__ float dpp_rol1(float v) { return __builtin_bit_cast(float, __builtin_amdgcn_update_dpp(0, __builtin_bit_cast(int, v), 0x12F, 0xF, 0xF, false)); }
;     __device__ __forceinline__ void operator()(const pg8::f32x4 (&acc)[2][2][4][2], const pg8::Unit& u, int wr, int wc, int fr, int fq) const {
;     ...
;                 const int rl = 16 * m + fr, gr = 62 * kb - 1 + rl;
;                 bool first, last; if (gr < ML) { const int t = gr & 8191; first = t == 0; last = t == 8191; } else { const int t = (gr - ML) & 255; first = t == 0; last = t == 255; }
;                 float res[8];
; #pragma unroll
;                 for (int c = 0; c < 8; ++c) {
;                     const int n = c >> 2, e = c & 3;
;                     const float x0 = acc[ai][0][m][n][e];
;                     const float ruC = dpp_ror1(x0), rdN = m < 3 ? dpp_rol1(acc[ai][0][m < 3 ? m + 1 : 3][n][e]) : 0.f;
;                     float xu = fr == 0 ? ruP[c] : ruC, xd = fr == 15 ? rdN : rdC[c];
;                     xu = first ? 0.f : xu; xd = last ? 0.f : xd;
;                     ruP[c] = ruC; rdC[c] = rdN;
;                     const float x = w0[c] * xu + w1[c] * x0 + w2[c] * xd + bb[c];
;                     const float u2 = -2.302208198f * (x + 0.044715f * x * x * x);
;                     res[c] = x * __builtin_amdgcn_rcpf(1.0f + __builtin_amdgcn_exp2f(u2)) * acc[ai][1][m][n][e];
;                 }
;                 if (rl >= 1 && rl <= 62 && gr < nrows) { v4u o; o.x = pk2(res[0], res[1]); o.y = pk2(res[2], res[3]); o.z = pk2(res[4], res[5]); o.w = pk2(res[6], res[7]);
;                     *(v4u*)(G + (size_t)gr * DFF + ch0) = o; }
.LBB0_1098:
	s_or_b64 exec, exec, s[80:81]
	s_nop 0
	v_add_u32_e32 v16, s65, v176
	v_cmp_gt_i32_e32 vcc, s86, v16
	v_mov_b32_dpp v23, v12 row_ror:1 row_mask:0xf bank_mask:0xf
	v_mov_b32_dpp v24, v13 row_ror:1 row_mask:0xf bank_mask:0xf
	v_mov_b32_dpp v21, v14 row_ror:1 row_mask:0xf bank_mask:0xf
	v_mov_b32_dpp v22, v15 row_ror:1 row_mask:0xf bank_mask:0xf
	v_mov_b32_dpp v19, v8 row_ror:1 row_mask:0xf bank_mask:0xf
	v_mov_b32_dpp v20, v9 row_ror:1 row_mask:0xf bank_mask:0xf
	v_mov_b32_dpp v17, v10 row_ror:1 row_mask:0xf bank_mask:0xf
	v_mov_b32_dpp v18, v11 row_ror:1 row_mask:0xf bank_mask:0xf
	s_and_b64 s[48:49], s[44:45], vcc
	s_and_saveexec_b64 s[52:53], s[48:49]
	s_cbranch_execz .LBB0_1100
	v_and_b32_e32 v25, 0x1fff, v16
	v_and_b32_e32 v26, 0xff, v16
	v_cmp_gt_i32_e32 vcc, s97, v16
	v_cmp_eq_u32_e64 s[48:49], s78, v25
	v_cndmask_b32_e64 v23, v23, v46, s[38:39]
	v_cndmask_b32_e32 v27, v26, v25, vcc
	v_cndmask_b32_e64 v25, 0, 1, s[48:49]
	v_cmp_eq_u32_e64 s[48:49], s12, v26
	v_cndmask_b32_e64 v24, v24, v47, s[38:39]
	s_waitcnt vmcnt(0)
	v_pk_mul_f32 v[12:13], v[12:13], v[92:93]
	v_cndmask_b32_e64 v26, 0, 1, s[48:49]
	v_cndmask_b32_e32 v25, v26, v25, vcc
	v_and_b32_e32 v26, 1, v25
	v_cmp_eq_u32_e64 s[48:49], 0, v27
	v_cmp_eq_u32_e32 vcc, 1, v26
	v_cndmask_b32_e64 v21, v21, v42, s[38:39]
	v_cndmask_b32_e64 v25, v24, 0, s[48:49]
	v_cndmask_b32_e64 v24, v23, 0, s[48:49]
	v_pk_fma_f32 v[12:13], v[76:77], v[24:25], v[12:13]
	v_cndmask_b32_e64 v25, v45, 0, vcc
	v_cndmask_b32_e64 v24, v44, 0, vcc
	v_pk_fma_f32 v[12:13], v[80:81], v[24:25], v[12:13]
	v_cndmask_b32_e64 v22, v22, v43, s[38:39]
	v_pk_add_f32 v[12:13], v[84:85], v[12:13]
	v_pk_mul_f32 v[14:15], v[14:15], v[94:95]
	v_mul_f32_e32 v23, 0x3d372713, v12
	v_mul_f32_e32 v23, v12, v23
	v_fma_f32 v23, v12, v23, v12
	v_mul_f32_e32 v23, 0xc0135761, v23
	v_exp_f32_e32 v23, v23
	v_mul_f32_e32 v24, 0x3d372713, v13
	v_mul_f32_e32 v24, v13, v24
	v_fma_f32 v24, v13, v24, v13
	v_mul_f32_e32 v24, 0xc0135761, v24
	v_add_f32_e32 v23, 1.0, v23
	v_exp_f32_e32 v25, v24
	v_rcp_f32_e32 v24, v23
	v_cndmask_b32_e64 v23, v22, 0, s[48:49]
	v_cndmask_b32_e64 v22, v21, 0, s[48:49]
	v_pk_fma_f32 v[14:15], v[78:79], v[22:23], v[14:15]
	v_cndmask_b32_e64 v23, v41, 0, vcc
	v_cndmask_b32_e64 v22, v40, 0, vcc
	v_pk_fma_f32 v[14:15], v[82:83], v[22:23], v[14:15]
	v_add_f32_e32 v25, 1.0, v25
	v_pk_add_f32 v[14:15], v[86:87], v[14:15]
	v_rcp_f32_e32 v25, v25
	v_mul_f32_e32 v21, 0x3d372713, v14
	v_mul_f32_e32 v21, v14, v21
	v_mul_f32_e32 v22, 0x3d372713, v15
	v_fma_f32 v21, v14, v21, v14
	v_mul_f32_e32 v22, v15, v22
	v_mul_f32_e32 v21, 0xc0135761, v21
	v_fma_f32 v22, v15, v22, v15
	v_exp_f32_e32 v21, v21
	v_mul_f32_e32 v22, 0xc0135761, v22
	v_exp_f32_e32 v23, v22
	v_pk_mul_f32 v[12:13], v[12:13], v[24:25]
	v_add_f32_e32 v21, 1.0, v21
	v_rcp_f32_e32 v22, v21
	v_add_f32_e32 v21, 1.0, v23
	v_rcp_f32_e32 v23, v21
	v_pk_mul_f32 v[4:5], v[4:5], v[12:13]
	v_cndmask_b32_e64 v17, v17, v34, s[38:39]
	v_cndmask_b32_e64 v18, v18, v35, s[38:39]
	v_pk_mul_f32 v[12:13], v[14:15], v[22:23]
	v_cndmask_b32_e64 v14, v19, v38, s[38:39]
	v_cndmask_b32_e64 v15, v20, v39, s[38:39]
	v_pk_mul_f32 v[8:9], v[8:9], v[68:69]
	v_cndmask_b32_e64 v15, v15, 0, s[48:49]
	v_cndmask_b32_e64 v14, v14, 0, s[48:49]
	v_pk_mul_f32 v[10:11], v[10:11], v[70:71]
	v_cndmask_b32_e64 v19, v18, 0, s[48:49]
	v_cndmask_b32_e64 v18, v17, 0, s[48:49]
	v_pk_fma_f32 v[8:9], v[56:57], v[14:15], v[8:9]
	v_cndmask_b32_e64 v15, v37, 0, vcc
	v_cndmask_b32_e64 v14, v36, 0, vcc
	v_pk_fma_f32 v[10:11], v[58:59], v[18:19], v[10:11]
	v_cndmask_b32_e64 v19, v33, 0, vcc
	v_cndmask_b32_e64 v18, v32, 0, vcc
	v_pk_fma_f32 v[8:9], v[60:61], v[14:15], v[8:9]
	v_pk_fma_f32 v[10:11], v[62:63], v[18:19], v[10:11]
	v_pk_add_f32 v[8:9], v[64:65], v[8:9]
	v_pk_add_f32 v[10:11], v[66:67], v[10:11]
	v_mul_f32_e32 v14, 0x3d372713, v8
	v_mul_f32_e32 v15, 0x3d372713, v9
	v_mul_f32_e32 v17, 0x3d372713, v10
	v_mul_f32_e32 v14, v8, v14
	v_mul_f32_e32 v15, v9, v15
	v_mul_f32_e32 v17, v10, v17
	v_mul_f32_e32 v18, 0x3d372713, v11
	v_fma_f32 v14, v8, v14, v8
	v_fma_f32 v15, v9, v15, v9
	v_fma_f32 v17, v10, v17, v10
	v_mul_f32_e32 v18, v11, v18
	v_mul_f32_e32 v14, 0xc0135761, v14
	v_mul_f32_e32 v15, 0xc0135761, v15
	v_mul_f32_e32 v17, 0xc0135761, v17
	v_fma_f32 v18, v11, v18, v11
	v_exp_f32_e32 v14, v14
	v_exp_f32_e32 v15, v15
	v_exp_f32_e32 v17, v17
	v_mul_f32_e32 v18, 0xc0135761, v18
	v_exp_f32_e32 v19, v18
	v_add_f32_e32 v14, 1.0, v14
	v_add_f32_e32 v15, 1.0, v15
	v_add_f32_e32 v17, 1.0, v17
	v_rcp_f32_e32 v14, v14
	v_rcp_f32_e32 v15, v15
	v_rcp_f32_e32 v18, v17
	v_add_f32_e32 v17, 1.0, v19
	v_rcp_f32_e32 v19, v17
	v_pk_mul_f32 v[8:9], v[8:9], v[14:15]
	v_pk_mul_f32 v[6:7], v[6:7], v[12:13]
	v_pk_mul_f32 v[8:9], v[0:1], v[8:9]
	v_pk_mul_f32 v[0:1], v[10:11], v[18:19]
	s_nop 0
	v_pk_mul_f32 v[10:11], v[2:3], v[0:1]
	v_cvt_pk_bf16_f32 v0, v4, v5
	v_mov_b64_e32 v[4:5], s[6:7]
	v_mad_i64_i32 v[4:5], s[48:49], v16, s1, v[4:5]
	v_cvt_pk_bf16_f32 v1, v6, v7
	v_cvt_pk_bf16_f32 v2, v8, v9
	v_cvt_pk_bf16_f32 v3, v10, v11
	v_lshl_add_u64 v[4:5], v[170:171], 1, v[4:5]
	global_store_dwordx4 v[4:5], v[0:3], off
